# v35 plus: removed the 24 back-to-back s_setprio 0 / s_setprio 1 pairs in the middle of the GEMM MFMA blocks
# speedup vs baseline: 1.0108x; 1.0009x over previous
; #define PG8_STAGE(bufoff, gbase, voff) do { _Pragma("unroll") for (int _i = 0; _i < 2; ++_i) \
;         __builtin_amdgcn_global_load_lds((const unsigned*)((const char*)(gbase) + (voff)[_i]), (PG8_LAS unsigned*)(lds + (bufoff) + ldsw + _i * 8192), 16, 0, 0); } while (0)
; #define PG8_LDA(dst, b, h) do { _Pragma("unroll") for (int m = 0; m < 4; ++m) _Pragma("unroll") for (int k = 0; k < 2; ++k) dst[m][k] = *(const PG8_LAS bf16x8*)(lds + PG8_SA(b, h) + aoff + m * 2048 + k * 1024); } while (0)
; #define PG8_LDB(dst, b, h) do { _Pragma("unroll") for (int n = 0; n < 2; ++n) _Pragma("unroll") for (int k = 0; k < 2; ++k) dst[n][k] = *(const PG8_LAS bf16x8*)(lds + PG8_SB(b, h) + boff + n * 2048 + k * 1024); } while (0)
; #define PG8_MMA(ai, bj, At, Bt) do { __builtin_amdgcn_s_setprio(1); _Pragma("unroll") for (int m = 0; m < 4; ++m) _Pragma("unroll") for (int n = 0; n < 2; ++n) _Pragma("unroll") for (int k = 0; k < 2; ++k) \
;         acc[ai][bj][m][n] = __builtin_amdgcn_mfma_f32_16x16x32_bf16(Bt[n][k], At[m][k], acc[ai][bj][m][n], 0, 0, 0); __builtin_amdgcn_s_setprio(0); } while (0)
; #define PG8_WAIT_V(n) asm volatile("s_waitcnt vmcnt(" #n ")" ::: "memory")
; #define PG8_WAIT_L(n) asm volatile("s_waitcnt lgkmcnt(" #n ")" ::: "memory")
; #define PG8_BAR __builtin_amdgcn_s_barrier()
; #define PG8_SCHED __builtin_amdgcn_sched_barrier(0)
; template <class Epi, class Sched, bool ALIGN_EPI = false, bool SP2 = false>
; __device__ __forceinline__ void gemm_phase(PG8_LAS unsigned char* lds, const Gemm g, const Sched& S, const Epi& E, int tid_in) {
;     ...
;             const bool last = (t == nt - 2);
;             const char* a1 = cA + (size_t)(t + 1) * kstep;
;             const char* a2 = last ? nA : cA + (size_t)(t + 2) * kstep; const char* b2 = last ? nB : cB + (size_t)(t + 2) * kstep;
;             const char* a3 = a2 + kstep; const char* b3 = b2 + kstep;
;             if (last && has_next) S.a_ready(nxt);
;             if constexpr (SP2) {
;             PG8_LDB(B0, 0, 0); PG8_LDB(B1, 0, 1); PG8_SCHED; PG8_LDA(At, 0, 0); PG8_STAGE(PG8_SA(1, 1), a1 + hstep, voffA);
;             PG8_WAIT_V(8); PG8_WAIT_L(0); PG8_BAR; PG8_MMA(0, 0, At, B0); PG8_MMA(0, 1, At, B1); PG8_BAR; PG8_SCHED;
;             PG8_LDA(At, 0, 1); PG8_STAGE(PG8_SB(0, 0), b2, voffB); PG8_STAGE(PG8_SB(0, 1), b2 + hstep, voffB); PG8_STAGE(PG8_SA(0, 0), a2, voffA);
.LBB0_296:
	s_add_u32 s20, s2, 0xfffc0080
	s_addc_u32 s21, s3, -1
	s_add_i32 s45, 0, 0x10000
	s_cmp_eq_u32 s44, 12
	s_cselect_b32 s23, s15, s21
	s_cselect_b32 s22, s40, s20
	s_cselect_b32 s21, s13, s43
	s_cselect_b32 s20, s41, s42
	s_add_i32 s48, 0, 0x14000
	v_add_u32_e32 v156, s45, v145
	v_add_u32_e32 v172, s48, v145
	ds_read_b128 v[140:143], v156
	ds_read_b128 v[148:151], v156 offset:1024
	ds_read_b128 v[152:155], v156 offset:2048
	ds_read_b128 v[156:159], v156 offset:3072
	ds_read_b128 v[160:163], v172
	ds_read_b128 v[164:167], v172 offset:1024
	ds_read_b128 v[168:171], v172 offset:2048
	ds_read_b128 v[172:175], v172 offset:3072
	v_lshl_add_u64 v[192:193], s[2:3], 0, v[136:137]
	s_add_i32 m0, s29, 0xc000
	ds_read_b128 v[176:179], v147
	ds_read_b128 v[180:183], v147 offset:1024
	ds_read_b128 v[184:187], v147 offset:2048
	ds_read_b128 v[188:191], v147 offset:3072
	ds_read_b128 v[204:207], v147 offset:4096
	ds_read_b128 v[208:211], v147 offset:5120
	ds_read_b128 v[212:215], v147 offset:6144
	ds_read_b128 v[216:219], v147 offset:7168
	global_load_lds_dwordx4 v[192:193], off
	v_lshl_add_u64 v[192:193], s[2:3], 0, v[138:139]
	s_add_i32 m0, s29, 0xe000
	s_nop 0
	global_load_lds_dwordx4 v[192:193], off
	s_waitcnt vmcnt(8)
	s_waitcnt lgkmcnt(0)
	s_barrier
	s_setprio 1
	s_waitcnt lgkmcnt(0)
	v_mfma_f32_16x16x32_bf16 v[126:129], v[140:143], v[176:179], v[126:129]
	v_mfma_f32_16x16x32_bf16 v[118:121], v[152:155], v[176:179], v[118:121]
	v_mfma_f32_16x16x32_bf16 v[110:113], v[140:143], v[184:187], v[110:113]
	v_mfma_f32_16x16x32_bf16 v[102:105], v[152:155], v[184:187], v[102:105]
	v_mfma_f32_16x16x32_bf16 v[94:97], v[140:143], v[204:207], v[94:97]
	v_mfma_f32_16x16x32_bf16 v[90:93], v[152:155], v[204:207], v[90:93]
	v_mfma_f32_16x16x32_bf16 v[78:81], v[140:143], v[212:215], v[78:81]
	v_mfma_f32_16x16x32_bf16 v[74:77], v[152:155], v[212:215], v[74:77]
	v_mfma_f32_16x16x32_bf16 v[126:129], v[148:151], v[180:183], v[126:129]
	v_mfma_f32_16x16x32_bf16 v[118:121], v[156:159], v[180:183], v[118:121]
	v_mfma_f32_16x16x32_bf16 v[110:113], v[148:151], v[188:191], v[110:113]
	v_mfma_f32_16x16x32_bf16 v[102:105], v[156:159], v[188:191], v[102:105]
	v_mfma_f32_16x16x32_bf16 v[94:97], v[148:151], v[208:211], v[94:97]
	v_mfma_f32_16x16x32_bf16 v[90:93], v[156:159], v[208:211], v[90:93]
	v_mfma_f32_16x16x32_bf16 v[78:81], v[148:151], v[216:219], v[78:81]
	v_mfma_f32_16x16x32_bf16 v[74:77], v[156:159], v[216:219], v[74:77]
	v_mfma_f32_16x16x32_bf16 v[122:125], v[160:163], v[176:179], v[122:125]
	v_mfma_f32_16x16x32_bf16 v[114:117], v[168:171], v[176:179], v[114:117]
	v_mfma_f32_16x16x32_bf16 v[106:109], v[160:163], v[184:187], v[106:109]
	v_mfma_f32_16x16x32_bf16 v[98:101], v[168:171], v[184:187], v[98:101]
	v_mfma_f32_16x16x32_bf16 v[86:89], v[160:163], v[204:207], v[86:89]
	v_mfma_f32_16x16x32_bf16 v[82:85], v[168:171], v[204:207], v[82:85]
	v_mfma_f32_16x16x32_bf16 v[70:73], v[160:163], v[212:215], v[70:73]
	v_mfma_f32_16x16x32_bf16 v[66:69], v[168:171], v[212:215], v[66:69]
	v_mfma_f32_16x16x32_bf16 v[122:125], v[164:167], v[180:183], v[122:125]
	v_mfma_f32_16x16x32_bf16 v[114:117], v[172:175], v[180:183], v[114:117]
	v_mfma_f32_16x16x32_bf16 v[106:109], v[164:167], v[188:191], v[106:109]
	v_mfma_f32_16x16x32_bf16 v[98:101], v[172:175], v[188:191], v[98:101]
	v_mfma_f32_16x16x32_bf16 v[86:89], v[164:167], v[208:211], v[86:89]
	v_mfma_f32_16x16x32_bf16 v[82:85], v[172:175], v[208:211], v[82:85]
	v_mfma_f32_16x16x32_bf16 v[70:73], v[164:167], v[216:219], v[70:73]
	v_mfma_f32_16x16x32_bf16 v[66:69], v[172:175], v[216:219], v[66:69]
	s_setprio 0
	s_barrier
	s_add_i32 s45, s45, s28
	v_lshl_add_u64 v[192:193], s[20:21], 0, v[32:33]
	s_mov_b32 m0, s45
	ds_read_b128 v[176:179], v147 offset:16384
	ds_read_b128 v[180:183], v147 offset:17408
	ds_read_b128 v[184:187], v147 offset:18432
	ds_read_b128 v[188:191], v147 offset:19456
	ds_read_b128 v[204:207], v147 offset:20480
	ds_read_b128 v[208:211], v147 offset:21504
	ds_read_b128 v[212:215], v147 offset:22528
	ds_read_b128 v[216:219], v147 offset:23552
	global_load_lds_dwordx4 v[192:193], off
	s_add_i32 m0, s45, 0x2000
	s_add_u32 s46, s20, 0x40000
	v_lshl_add_u64 v[220:221], s[20:21], 0, v[130:131]
	s_addc_u32 s47, s21, 0
	s_add_i32 s45, s48, s28
	global_load_lds_dwordx4 v[220:221], off
	v_lshl_add_u64 v[222:223], s[46:47], 0, v[32:33]
	s_mov_b32 m0, s45
	v_lshl_add_u64 v[224:225], s[22:23], 0, v[132:133]
	global_load_lds_dwordx4 v[222:223], off
	v_lshl_add_u64 v[222:223], s[46:47], 0, v[130:131]
	s_add_i32 m0, s45, 0x2000
	s_nop 0
	global_load_lds_dwordx4 v[222:223], off
	v_lshl_add_u64 v[222:223], s[22:23], 0, v[134:135]
	s_mov_b32 m0, s29
	s_nop 0
	global_load_lds_dwordx4 v[222:223], off
	s_mov_b32 m0, s30
	s_nop 0
	global_load_lds_dwordx4 v[224:225], off
	s_waitcnt vmcnt(8)
	s_waitcnt lgkmcnt(0)
	s_barrier
; #define PG8_STAGE(bufoff, gbase, voff) do { _Pragma("unroll") for (int _i = 0; _i < 2; ++_i) \
;         __builtin_amdgcn_global_load_lds((const unsigned*)((const char*)(gbase) + (voff)[_i]), (PG8_LAS unsigned*)(lds + (bufoff) + ldsw + _i * 8192), 16, 0, 0); } while (0)
; #define PG8_LDA(dst, b, h) do { _Pragma("unroll") for (int m = 0; m < 4; ++m) _Pragma("unroll") for (int k = 0; k < 2; ++k) dst[m][k] = *(const PG8_LAS bf16x8*)(lds + PG8_SA(b, h) + aoff + m * 2048 + k * 1024); } while (0)
; #define PG8_LDB(dst, b, h) do { _Pragma("unroll") for (int n = 0; n < 2; ++n) _Pragma("unroll") for (int k = 0; k < 2; ++k) dst[n][k] = *(const PG8_LAS bf16x8*)(lds + PG8_SB(b, h) + boff + n * 2048 + k * 1024); } while (0)
; #define PG8_MMA(ai, bj, At, Bt) do { __builtin_amdgcn_s_setprio(1); _Pragma("unroll") for (int m = 0; m < 4; ++m) _Pragma("unroll") for (int n = 0; n < 2; ++n) _Pragma("unroll") for (int k = 0; k < 2; ++k) \
;         acc[ai][bj][m][n] = __builtin_amdgcn_mfma_f32_16x16x32_bf16(Bt[n][k], At[m][k], acc[ai][bj][m][n], 0, 0, 0); __builtin_amdgcn_s_setprio(0); } while (0)
; #define PG8_WAIT_V(n) asm volatile("s_waitcnt vmcnt(" #n ")" ::: "memory")
; #define PG8_WAIT_L(n) asm volatile("s_waitcnt lgkmcnt(" #n ")" ::: "memory")
; #define PG8_BAR __builtin_amdgcn_s_barrier()
; #define PG8_SCHED __builtin_amdgcn_sched_barrier(0)
; template <class Epi, class Sched, bool ALIGN_EPI = false, bool SP2 = false>
; __device__ __forceinline__ void gemm_phase(PG8_LAS unsigned char* lds, const Gemm g, const Sched& S, const Epi& E, int tid_in) {
;     ...
;             PG8_WAIT_V(8); PG8_WAIT_L(0); PG8_BAR; PG8_MMA(1, 0, At, B0); PG8_MMA(1, 1, At, B1); PG8_BAR; PG8_SCHED;
;             PG8_LDB(B0, 1, 0); PG8_LDB(B1, 1, 1); PG8_SCHED; PG8_LDA(At, 1, 0); PG8_STAGE(PG8_SA(0, 1), a2 + hstep, voffA);
;             PG8_WAIT_V(8); PG8_WAIT_L(0); PG8_BAR; PG8_MMA(0, 0, At, B0); PG8_MMA(0, 1, At, B1); PG8_BAR; PG8_SCHED;
	s_setprio 1
	s_waitcnt lgkmcnt(0)
	v_mfma_f32_16x16x32_bf16 v[62:65], v[140:143], v[176:179], v[62:65]
	v_mfma_f32_16x16x32_bf16 v[58:61], v[152:155], v[176:179], v[58:61]
	v_mfma_f32_16x16x32_bf16 v[46:49], v[140:143], v[184:187], v[46:49]
	v_mfma_f32_16x16x32_bf16 v[42:45], v[152:155], v[184:187], v[42:45]
	v_mfma_f32_16x16x32_bf16 v[28:31], v[140:143], v[204:207], v[28:31]
	v_mfma_f32_16x16x32_bf16 v[24:27], v[152:155], v[204:207], v[24:27]
	v_mfma_f32_16x16x32_bf16 v[12:15], v[140:143], v[212:215], v[12:15]
	v_mfma_f32_16x16x32_bf16 v[8:11], v[152:155], v[212:215], v[8:11]
	v_mfma_f32_16x16x32_bf16 v[62:65], v[148:151], v[180:183], v[62:65]
	v_mfma_f32_16x16x32_bf16 v[58:61], v[156:159], v[180:183], v[58:61]
	v_mfma_f32_16x16x32_bf16 v[46:49], v[148:151], v[188:191], v[46:49]
	v_mfma_f32_16x16x32_bf16 v[42:45], v[156:159], v[188:191], v[42:45]
	v_mfma_f32_16x16x32_bf16 v[28:31], v[148:151], v[208:211], v[28:31]
	v_mfma_f32_16x16x32_bf16 v[24:27], v[156:159], v[208:211], v[24:27]
	v_mfma_f32_16x16x32_bf16 v[12:15], v[148:151], v[216:219], v[12:15]
	v_mfma_f32_16x16x32_bf16 v[8:11], v[156:159], v[216:219], v[8:11]
	v_mfma_f32_16x16x32_bf16 v[54:57], v[160:163], v[176:179], v[54:57]
	v_mfma_f32_16x16x32_bf16 v[50:53], v[168:171], v[176:179], v[50:53]
	v_mfma_f32_16x16x32_bf16 v[38:41], v[160:163], v[184:187], v[38:41]
	v_mfma_f32_16x16x32_bf16 v[34:37], v[168:171], v[184:187], v[34:37]
	v_mfma_f32_16x16x32_bf16 v[20:23], v[160:163], v[204:207], v[20:23]
	v_mfma_f32_16x16x32_bf16 v[16:19], v[168:171], v[204:207], v[16:19]
	v_mfma_f32_16x16x32_bf16 v[4:7], v[160:163], v[212:215], v[4:7]
	v_mfma_f32_16x16x32_bf16 v[0:3], v[168:171], v[212:215], v[0:3]
	v_mfma_f32_16x16x32_bf16 v[54:57], v[164:167], v[180:183], v[54:57]
	v_mfma_f32_16x16x32_bf16 v[50:53], v[172:175], v[180:183], v[50:53]
	v_mfma_f32_16x16x32_bf16 v[38:41], v[164:167], v[188:191], v[38:41]
	v_mfma_f32_16x16x32_bf16 v[34:37], v[172:175], v[188:191], v[34:37]
	v_mfma_f32_16x16x32_bf16 v[20:23], v[164:167], v[208:211], v[20:23]
	v_mfma_f32_16x16x32_bf16 v[16:19], v[172:175], v[208:211], v[16:19]
	v_mfma_f32_16x16x32_bf16 v[4:7], v[164:167], v[216:219], v[4:7]
	v_mfma_f32_16x16x32_bf16 v[0:3], v[172:175], v[216:219], v[0:3]
	s_setprio 0
	s_barrier
	s_add_i32 s45, 0, 0x18000
	s_add_i32 s46, 0, 0x1c000
	v_add_u32_e32 v156, s45, v145
	v_add_u32_e32 v172, s46, v145
	ds_read_b128 v[140:143], v156
	ds_read_b128 v[148:151], v156 offset:1024
	ds_read_b128 v[152:155], v156 offset:2048
	ds_read_b128 v[156:159], v156 offset:3072
	ds_read_b128 v[160:163], v172
	ds_read_b128 v[164:167], v172 offset:1024
	ds_read_b128 v[168:171], v172 offset:2048
	ds_read_b128 v[172:175], v172 offset:3072
	s_add_u32 s22, s22, 0x40000
	s_addc_u32 s23, s23, 0
	s_mov_b32 m0, s31
	v_lshl_add_u64 v[226:227], s[22:23], 0, v[134:135]
	ds_read_b128 v[176:179], v147 offset:32768
	ds_read_b128 v[180:183], v147 offset:33792
	ds_read_b128 v[184:187], v147 offset:34816
	ds_read_b128 v[188:191], v147 offset:35840
	ds_read_b128 v[204:207], v147 offset:36864
	ds_read_b128 v[208:211], v147 offset:37888
	ds_read_b128 v[212:215], v147 offset:38912
	ds_read_b128 v[216:219], v147 offset:39936
	global_load_lds_dwordx4 v[226:227], off
	v_lshl_add_u64 v[226:227], s[22:23], 0, v[132:133]
	s_mov_b32 m0, s34
	s_nop 0
	global_load_lds_dwordx4 v[226:227], off
	s_waitcnt vmcnt(8)
	s_waitcnt lgkmcnt(0)
	s_barrier
	s_setprio 1
	s_waitcnt lgkmcnt(0)
	v_mfma_f32_16x16x32_bf16 v[126:129], v[140:143], v[176:179], v[126:129]
	v_mfma_f32_16x16x32_bf16 v[118:121], v[152:155], v[176:179], v[118:121]
	v_mfma_f32_16x16x32_bf16 v[110:113], v[140:143], v[184:187], v[110:113]
	v_mfma_f32_16x16x32_bf16 v[102:105], v[152:155], v[184:187], v[102:105]
	v_mfma_f32_16x16x32_bf16 v[94:97], v[140:143], v[204:207], v[94:97]
	v_mfma_f32_16x16x32_bf16 v[90:93], v[152:155], v[204:207], v[90:93]
	v_mfma_f32_16x16x32_bf16 v[78:81], v[140:143], v[212:215], v[78:81]
	v_mfma_f32_16x16x32_bf16 v[74:77], v[152:155], v[212:215], v[74:77]
	v_mfma_f32_16x16x32_bf16 v[126:129], v[148:151], v[180:183], v[126:129]
	v_mfma_f32_16x16x32_bf16 v[118:121], v[156:159], v[180:183], v[118:121]
	v_mfma_f32_16x16x32_bf16 v[110:113], v[148:151], v[188:191], v[110:113]
	v_mfma_f32_16x16x32_bf16 v[102:105], v[156:159], v[188:191], v[102:105]
	v_mfma_f32_16x16x32_bf16 v[94:97], v[148:151], v[208:211], v[94:97]
	v_mfma_f32_16x16x32_bf16 v[90:93], v[156:159], v[208:211], v[90:93]
	v_mfma_f32_16x16x32_bf16 v[78:81], v[148:151], v[216:219], v[78:81]
	v_mfma_f32_16x16x32_bf16 v[74:77], v[156:159], v[216:219], v[74:77]
	v_mfma_f32_16x16x32_bf16 v[122:125], v[160:163], v[176:179], v[122:125]
	v_mfma_f32_16x16x32_bf16 v[114:117], v[168:171], v[176:179], v[114:117]
	v_mfma_f32_16x16x32_bf16 v[106:109], v[160:163], v[184:187], v[106:109]
	v_mfma_f32_16x16x32_bf16 v[98:101], v[168:171], v[184:187], v[98:101]
	v_mfma_f32_16x16x32_bf16 v[86:89], v[160:163], v[204:207], v[86:89]
	v_mfma_f32_16x16x32_bf16 v[82:85], v[168:171], v[204:207], v[82:85]
	v_mfma_f32_16x16x32_bf16 v[70:73], v[160:163], v[212:215], v[70:73]
	v_mfma_f32_16x16x32_bf16 v[66:69], v[168:171], v[212:215], v[66:69]
	v_mfma_f32_16x16x32_bf16 v[122:125], v[164:167], v[180:183], v[122:125]
	v_mfma_f32_16x16x32_bf16 v[114:117], v[172:175], v[180:183], v[114:117]
	v_mfma_f32_16x16x32_bf16 v[106:109], v[164:167], v[188:191], v[106:109]
	v_mfma_f32_16x16x32_bf16 v[98:101], v[172:175], v[188:191], v[98:101]
	v_mfma_f32_16x16x32_bf16 v[86:89], v[164:167], v[208:211], v[86:89]
	v_mfma_f32_16x16x32_bf16 v[82:85], v[172:175], v[208:211], v[82:85]
	v_mfma_f32_16x16x32_bf16 v[70:73], v[164:167], v[216:219], v[70:73]
	v_mfma_f32_16x16x32_bf16 v[66:69], v[172:175], v[216:219], v[66:69]
	s_setprio 0
	s_barrier
; #define PG8_STAGE(bufoff, gbase, voff) do { _Pragma("unroll") for (int _i = 0; _i < 2; ++_i) \
;         __builtin_amdgcn_global_load_lds((const unsigned*)((const char*)(gbase) + (voff)[_i]), (PG8_LAS unsigned*)(lds + (bufoff) + ldsw + _i * 8192), 16, 0, 0); } while (0)
; #define PG8_LDA(dst, b, h) do { _Pragma("unroll") for (int m = 0; m < 4; ++m) _Pragma("unroll") for (int k = 0; k < 2; ++k) dst[m][k] = *(const PG8_LAS bf16x8*)(lds + PG8_SA(b, h) + aoff + m * 2048 + k * 1024); } while (0)
; #define PG8_MMA(ai, bj, At, Bt) do { __builtin_amdgcn_s_setprio(1); _Pragma("unroll") for (int m = 0; m < 4; ++m) _Pragma("unroll") for (int n = 0; n < 2; ++n) _Pragma("unroll") for (int k = 0; k < 2; ++k) \
;         acc[ai][bj][m][n] = __builtin_amdgcn_mfma_f32_16x16x32_bf16(Bt[n][k], At[m][k], acc[ai][bj][m][n], 0, 0, 0); __builtin_amdgcn_s_setprio(0); } while (0)
; #define PG8_WAIT_V(n) asm volatile("s_waitcnt vmcnt(" #n ")" ::: "memory")
; #define PG8_WAIT_L(n) asm volatile("s_waitcnt lgkmcnt(" #n ")" ::: "memory")
; #define PG8_BAR __builtin_amdgcn_s_barrier()
; #define PG8_SCHED __builtin_amdgcn_sched_barrier(0)
; template <class Epi, class Sched, bool ALIGN_EPI = false, bool SP2 = false>
; __device__ __forceinline__ void gemm_phase(PG8_LAS unsigned char* lds, const Gemm g, const Sched& S, const Epi& E, int tid_in) {
;     ...
;             PG8_LDA(At, 1, 1); PG8_STAGE(PG8_SB(1, 0), b3, voffB); PG8_STAGE(PG8_SB(1, 1), b3 + hstep, voffB); PG8_STAGE(PG8_SA(1, 0), a3, voffA);
;             PG8_WAIT_V(8); PG8_WAIT_L(0); PG8_BAR; PG8_MMA(1, 0, At, B0); PG8_MMA(1, 1, At, B1); PG8_BAR; PG8_SCHED;
;     ...
;         if constexpr (ALIGN_EPI) { if (wr == 0) PG8_BAR; }
	s_add_i32 s22, s45, s28
	v_lshl_add_u64 v[192:193], v[192:193], 0, s[84:85]
	s_mov_b32 m0, s22
	ds_read_b128 v[176:179], v147 offset:49152
	ds_read_b128 v[180:183], v147 offset:50176
	ds_read_b128 v[184:187], v147 offset:51200
	ds_read_b128 v[188:191], v147 offset:52224
	ds_read_b128 v[204:207], v147 offset:53248
	ds_read_b128 v[208:211], v147 offset:54272
	ds_read_b128 v[212:215], v147 offset:55296
	ds_read_b128 v[216:219], v147 offset:56320
	global_load_lds_dwordx4 v[192:193], off
	s_add_i32 m0, s22, 0x2000
	s_add_u32 s20, s20, 0x40080
	v_lshl_add_u64 v[192:193], v[220:221], 0, s[84:85]
	s_addc_u32 s21, s21, 0
	s_add_i32 s22, s46, s28
	global_load_lds_dwordx4 v[192:193], off
	v_lshl_add_u64 v[192:193], s[20:21], 0, v[32:33]
	s_mov_b32 m0, s22
	s_nop 0
	global_load_lds_dwordx4 v[192:193], off
	v_lshl_add_u64 v[192:193], s[20:21], 0, v[130:131]
	s_add_i32 m0, s22, 0x2000
	s_nop 0
	global_load_lds_dwordx4 v[192:193], off
	v_lshl_add_u64 v[192:193], v[222:223], 0, s[84:85]
	s_mov_b32 m0, s35
	s_nop 0
	global_load_lds_dwordx4 v[192:193], off
	v_lshl_add_u64 v[192:193], v[224:225], 0, s[84:85]
	s_mov_b32 m0, s36
	s_nop 0
	global_load_lds_dwordx4 v[192:193], off
	s_waitcnt vmcnt(8)
	s_waitcnt lgkmcnt(0)
	s_barrier
	s_setprio 1
	s_waitcnt lgkmcnt(0)
	v_mfma_f32_16x16x32_bf16 v[62:65], v[140:143], v[176:179], v[62:65]
	v_mfma_f32_16x16x32_bf16 v[58:61], v[152:155], v[176:179], v[58:61]
	v_mfma_f32_16x16x32_bf16 v[46:49], v[140:143], v[184:187], v[46:49]
	v_mfma_f32_16x16x32_bf16 v[42:45], v[152:155], v[184:187], v[42:45]
	v_mfma_f32_16x16x32_bf16 v[28:31], v[140:143], v[204:207], v[28:31]
	v_mfma_f32_16x16x32_bf16 v[24:27], v[152:155], v[204:207], v[24:27]
	v_mfma_f32_16x16x32_bf16 v[12:15], v[140:143], v[212:215], v[12:15]
	v_mfma_f32_16x16x32_bf16 v[8:11], v[152:155], v[212:215], v[8:11]
	v_mfma_f32_16x16x32_bf16 v[62:65], v[148:151], v[180:183], v[62:65]
	v_mfma_f32_16x16x32_bf16 v[58:61], v[156:159], v[180:183], v[58:61]
	v_mfma_f32_16x16x32_bf16 v[46:49], v[148:151], v[188:191], v[46:49]
	v_mfma_f32_16x16x32_bf16 v[42:45], v[156:159], v[188:191], v[42:45]
	v_mfma_f32_16x16x32_bf16 v[28:31], v[148:151], v[208:211], v[28:31]
	v_mfma_f32_16x16x32_bf16 v[24:27], v[156:159], v[208:211], v[24:27]
	v_mfma_f32_16x16x32_bf16 v[12:15], v[148:151], v[216:219], v[12:15]
	v_mfma_f32_16x16x32_bf16 v[8:11], v[156:159], v[216:219], v[8:11]
	v_mfma_f32_16x16x32_bf16 v[54:57], v[160:163], v[176:179], v[54:57]
	v_mfma_f32_16x16x32_bf16 v[50:53], v[168:171], v[176:179], v[50:53]
	v_mfma_f32_16x16x32_bf16 v[38:41], v[160:163], v[184:187], v[38:41]
	v_mfma_f32_16x16x32_bf16 v[34:37], v[168:171], v[184:187], v[34:37]
	v_mfma_f32_16x16x32_bf16 v[20:23], v[160:163], v[204:207], v[20:23]
	v_mfma_f32_16x16x32_bf16 v[16:19], v[168:171], v[204:207], v[16:19]
	v_mfma_f32_16x16x32_bf16 v[4:7], v[160:163], v[212:215], v[4:7]
	v_mfma_f32_16x16x32_bf16 v[0:3], v[168:171], v[212:215], v[0:3]
	v_mfma_f32_16x16x32_bf16 v[54:57], v[164:167], v[180:183], v[54:57]
	v_mfma_f32_16x16x32_bf16 v[50:53], v[172:175], v[180:183], v[50:53]
	v_mfma_f32_16x16x32_bf16 v[38:41], v[164:167], v[188:191], v[38:41]
	v_mfma_f32_16x16x32_bf16 v[34:37], v[172:175], v[188:191], v[34:37]
	v_mfma_f32_16x16x32_bf16 v[20:23], v[164:167], v[208:211], v[20:23]
	v_mfma_f32_16x16x32_bf16 v[16:19], v[172:175], v[208:211], v[16:19]
	v_mfma_f32_16x16x32_bf16 v[4:7], v[164:167], v[216:219], v[4:7]
	v_mfma_f32_16x16x32_bf16 v[0:3], v[172:175], v[216:219], v[0:3]
	s_setprio 0
	s_barrier
	s_add_i32 s44, s44, 2
	s_add_u32 s2, s2, 0x100
	s_addc_u32 s3, s3, 0
	s_add_u32 s42, s42, 0x100
	s_addc_u32 s43, s43, 0
	s_cmp_gt_u32 s44, 13
	s_cbranch_scc0 .LBB0_296
	s_and_b64 vcc, exec, s[10:11]
	s_cbranch_vccz .LBB0_299
	s_barrier

; #define PG8_STAGE(bufoff, gbase, voff) do { _Pragma("unroll") for (int _i = 0; _i < 2; ++_i) \
;         __builtin_amdgcn_global_load_lds((const unsigned*)((const char*)(gbase) + (voff)[_i]), (PG8_LAS unsigned*)(lds + (bufoff) + ldsw + _i * 8192), 16, 0, 0); } while (0)
; #define PG8_LDA(dst, b, h) do { _Pragma("unroll") for (int m = 0; m < 4; ++m) _Pragma("unroll") for (int k = 0; k < 2; ++k) dst[m][k] = *(const PG8_LAS bf16x8*)(lds + PG8_SA(b, h) + aoff + m * 2048 + k * 1024); } while (0)
; #define PG8_LDB(dst, b, h) do { _Pragma("unroll") for (int n = 0; n < 2; ++n) _Pragma("unroll") for (int k = 0; k < 2; ++k) dst[n][k] = *(const PG8_LAS bf16x8*)(lds + PG8_SB(b, h) + boff + n * 2048 + k * 1024); } while (0)
; #define PG8_MMA(ai, bj, At, Bt) do { __builtin_amdgcn_s_setprio(1); _Pragma("unroll") for (int m = 0; m < 4; ++m) _Pragma("unroll") for (int n = 0; n < 2; ++n) _Pragma("unroll") for (int k = 0; k < 2; ++k) \
;         acc[ai][bj][m][n] = __builtin_amdgcn_mfma_f32_16x16x32_bf16(Bt[n][k], At[m][k], acc[ai][bj][m][n], 0, 0, 0); __builtin_amdgcn_s_setprio(0); } while (0)
; #define PG8_WAIT_V(n) asm volatile("s_waitcnt vmcnt(" #n ")" ::: "memory")
; #define PG8_WAIT_L(n) asm volatile("s_waitcnt lgkmcnt(" #n ")" ::: "memory")
; #define PG8_BAR __builtin_amdgcn_s_barrier()
; #define PG8_SCHED __builtin_amdgcn_sched_barrier(0)
; template <class Epi, class Sched, bool ALIGN_EPI = false, bool SP2 = false>
; __device__ __forceinline__ void gemm_phase(PG8_LAS unsigned char* lds, const Gemm g, const Sched& S, const Epi& E, int tid_in) {
;     ...
;             const bool last = (t == nt - 2);
;             const char* a1 = cA + (size_t)(t + 1) * kstep;
;             const char* a2 = last ? nA : cA + (size_t)(t + 2) * kstep; const char* b2 = last ? nB : cB + (size_t)(t + 2) * kstep;
;             const char* a3 = a2 + kstep; const char* b3 = b2 + kstep;
;             if (last && has_next) S.a_ready(nxt);
;             if constexpr (SP2) {
;             PG8_LDB(B0, 0, 0); PG8_LDB(B1, 0, 1); PG8_SCHED; PG8_LDA(At, 0, 0); PG8_STAGE(PG8_SA(1, 1), a1 + hstep, voffA);
;             PG8_WAIT_V(8); PG8_WAIT_L(0); PG8_BAR; PG8_MMA(0, 0, At, B0); PG8_MMA(0, 1, At, B1); PG8_BAR; PG8_SCHED;
;             PG8_LDA(At, 0, 1); PG8_STAGE(PG8_SB(0, 0), b2, voffB); PG8_STAGE(PG8_SB(0, 1), b2 + hstep, voffB); PG8_STAGE(PG8_SA(0, 0), a2, voffA);
.LBB0_340:
	s_add_u32 s24, s2, 0x100
	s_addc_u32 s25, s3, 0
	s_add_i32 s51, 0, 0x10000
	s_cmp_eq_u32 s50, 40
	s_cselect_b32 s29, s9, s25
	s_cselect_b32 s28, s8, s24
	s_cselect_b32 s27, s23, s49
	s_cselect_b32 s26, s22, s48
	s_add_i32 s53, 0, 0x14000
	v_add_u32_e32 v142, s51, v211
	v_add_u32_e32 v158, s53, v211
	ds_read_b128 v[130:133], v142
	ds_read_b128 v[134:137], v142 offset:1024
	ds_read_b128 v[138:141], v142 offset:2048
	ds_read_b128 v[142:145], v142 offset:3072
	ds_read_b128 v[146:149], v158
	ds_read_b128 v[150:153], v158 offset:1024
	ds_read_b128 v[154:157], v158 offset:2048
	ds_read_b128 v[158:161], v158 offset:3072
	v_lshl_add_u64 v[192:193], s[2:3], 0, v[184:185]
	s_add_i32 m0, s37, 0xc000
	ds_read_b128 v[162:165], v213
	ds_read_b128 v[166:169], v213 offset:1024
	ds_read_b128 v[170:173], v213 offset:2048
	ds_read_b128 v[174:177], v213 offset:3072
	ds_read_b128 v[188:191], v213 offset:4096
	ds_read_b128 v[204:207], v213 offset:5120
	ds_read_b128 v[214:217], v213 offset:6144
	ds_read_b128 v[218:221], v213 offset:7168
	global_load_lds_dwordx4 v[192:193], off
	v_lshl_add_u64 v[192:193], s[2:3], 0, v[186:187]
	s_add_i32 m0, s37, 0xe000
	s_nop 0
	global_load_lds_dwordx4 v[192:193], off
	s_waitcnt vmcnt(8)
	s_waitcnt lgkmcnt(0)
	s_barrier
	s_setprio 1
	s_waitcnt lgkmcnt(0)
	v_mfma_f32_16x16x32_bf16 v[126:129], v[130:133], v[162:165], v[126:129]
	v_mfma_f32_16x16x32_bf16 v[122:125], v[138:141], v[162:165], v[122:125]
	v_mfma_f32_16x16x32_bf16 v[110:113], v[130:133], v[170:173], v[110:113]
	v_mfma_f32_16x16x32_bf16 v[106:109], v[138:141], v[170:173], v[106:109]
	v_mfma_f32_16x16x32_bf16 v[94:97], v[130:133], v[188:191], v[94:97]
	v_mfma_f32_16x16x32_bf16 v[90:93], v[138:141], v[188:191], v[90:93]
	v_mfma_f32_16x16x32_bf16 v[78:81], v[130:133], v[214:217], v[78:81]
	v_mfma_f32_16x16x32_bf16 v[74:77], v[138:141], v[214:217], v[74:77]
	v_mfma_f32_16x16x32_bf16 v[126:129], v[134:137], v[166:169], v[126:129]
	v_mfma_f32_16x16x32_bf16 v[122:125], v[142:145], v[166:169], v[122:125]
	v_mfma_f32_16x16x32_bf16 v[110:113], v[134:137], v[174:177], v[110:113]
	v_mfma_f32_16x16x32_bf16 v[106:109], v[142:145], v[174:177], v[106:109]
	v_mfma_f32_16x16x32_bf16 v[94:97], v[134:137], v[204:207], v[94:97]
	v_mfma_f32_16x16x32_bf16 v[90:93], v[142:145], v[204:207], v[90:93]
	v_mfma_f32_16x16x32_bf16 v[78:81], v[134:137], v[218:221], v[78:81]
	v_mfma_f32_16x16x32_bf16 v[74:77], v[142:145], v[218:221], v[74:77]
	v_mfma_f32_16x16x32_bf16 v[118:121], v[146:149], v[162:165], v[118:121]
	v_mfma_f32_16x16x32_bf16 v[114:117], v[154:157], v[162:165], v[114:117]
	v_mfma_f32_16x16x32_bf16 v[102:105], v[146:149], v[170:173], v[102:105]
	v_mfma_f32_16x16x32_bf16 v[98:101], v[154:157], v[170:173], v[98:101]
	v_mfma_f32_16x16x32_bf16 v[86:89], v[146:149], v[188:191], v[86:89]
	v_mfma_f32_16x16x32_bf16 v[82:85], v[154:157], v[188:191], v[82:85]
	v_mfma_f32_16x16x32_bf16 v[70:73], v[146:149], v[214:217], v[70:73]
	v_mfma_f32_16x16x32_bf16 v[66:69], v[154:157], v[214:217], v[66:69]
	v_mfma_f32_16x16x32_bf16 v[118:121], v[150:153], v[166:169], v[118:121]
	v_mfma_f32_16x16x32_bf16 v[114:117], v[158:161], v[166:169], v[114:117]
	v_mfma_f32_16x16x32_bf16 v[102:105], v[150:153], v[174:177], v[102:105]
	v_mfma_f32_16x16x32_bf16 v[98:101], v[158:161], v[174:177], v[98:101]
	v_mfma_f32_16x16x32_bf16 v[86:89], v[150:153], v[204:207], v[86:89]
	v_mfma_f32_16x16x32_bf16 v[82:85], v[158:161], v[204:207], v[82:85]
	v_mfma_f32_16x16x32_bf16 v[70:73], v[150:153], v[218:221], v[70:73]
	v_mfma_f32_16x16x32_bf16 v[66:69], v[158:161], v[218:221], v[66:69]
	s_setprio 0
	s_barrier
	s_add_i32 s2, s51, s36
	v_lshl_add_u64 v[192:193], s[26:27], 0, v[32:33]
	s_mov_b32 m0, s2
	ds_read_b128 v[162:165], v213 offset:16384
	ds_read_b128 v[166:169], v213 offset:17408
	ds_read_b128 v[170:173], v213 offset:18432
	ds_read_b128 v[174:177], v213 offset:19456
	ds_read_b128 v[188:191], v213 offset:20480
	ds_read_b128 v[204:207], v213 offset:21504
	ds_read_b128 v[214:217], v213 offset:22528
	ds_read_b128 v[218:221], v213 offset:23552
	global_load_lds_dwordx4 v[192:193], off
	s_add_i32 m0, s2, 0x2000
	s_add_u32 s2, s26, 0xb0000
	v_lshl_add_u64 v[208:209], s[26:27], 0, v[178:179]
	s_addc_u32 s3, s27, 0
	s_add_i32 s51, s53, s36
	global_load_lds_dwordx4 v[208:209], off
	v_lshl_add_u64 v[222:223], s[2:3], 0, v[32:33]
	s_mov_b32 m0, s51
	v_lshl_add_u64 v[224:225], s[28:29], 0, v[180:181]
	global_load_lds_dwordx4 v[222:223], off
	v_lshl_add_u64 v[222:223], s[2:3], 0, v[178:179]
	s_add_i32 m0, s51, 0x2000
	s_nop 0
	global_load_lds_dwordx4 v[222:223], off
	v_lshl_add_u64 v[222:223], s[28:29], 0, v[182:183]
	s_mov_b32 m0, s37
	s_nop 0
	global_load_lds_dwordx4 v[222:223], off
	s_mov_b32 m0, s38
	s_nop 0
	global_load_lds_dwordx4 v[224:225], off
	s_waitcnt vmcnt(8)
	s_waitcnt lgkmcnt(0)
	s_barrier
; #define PG8_STAGE(bufoff, gbase, voff) do { _Pragma("unroll") for (int _i = 0; _i < 2; ++_i) \
;         __builtin_amdgcn_global_load_lds((const unsigned*)((const char*)(gbase) + (voff)[_i]), (PG8_LAS unsigned*)(lds + (bufoff) + ldsw + _i * 8192), 16, 0, 0); } while (0)
; #define PG8_LDA(dst, b, h) do { _Pragma("unroll") for (int m = 0; m < 4; ++m) _Pragma("unroll") for (int k = 0; k < 2; ++k) dst[m][k] = *(const PG8_LAS bf16x8*)(lds + PG8_SA(b, h) + aoff + m * 2048 + k * 1024); } while (0)
; #define PG8_LDB(dst, b, h) do { _Pragma("unroll") for (int n = 0; n < 2; ++n) _Pragma("unroll") for (int k = 0; k < 2; ++k) dst[n][k] = *(const PG8_LAS bf16x8*)(lds + PG8_SB(b, h) + boff + n * 2048 + k * 1024); } while (0)
; #define PG8_MMA(ai, bj, At, Bt) do { __builtin_amdgcn_s_setprio(1); _Pragma("unroll") for (int m = 0; m < 4; ++m) _Pragma("unroll") for (int n = 0; n < 2; ++n) _Pragma("unroll") for (int k = 0; k < 2; ++k) \
;         acc[ai][bj][m][n] = __builtin_amdgcn_mfma_f32_16x16x32_bf16(Bt[n][k], At[m][k], acc[ai][bj][m][n], 0, 0, 0); __builtin_amdgcn_s_setprio(0); } while (0)
; #define PG8_WAIT_V(n) asm volatile("s_waitcnt vmcnt(" #n ")" ::: "memory")
; #define PG8_WAIT_L(n) asm volatile("s_waitcnt lgkmcnt(" #n ")" ::: "memory")
; #define PG8_BAR __builtin_amdgcn_s_barrier()
; #define PG8_SCHED __builtin_amdgcn_sched_barrier(0)
; template <class Epi, class Sched, bool ALIGN_EPI = false, bool SP2 = false>
; __device__ __forceinline__ void gemm_phase(PG8_LAS unsigned char* lds, const Gemm g, const Sched& S, const Epi& E, int tid_in) {
;     ...
;             PG8_WAIT_V(8); PG8_WAIT_L(0); PG8_BAR; PG8_MMA(1, 0, At, B0); PG8_MMA(1, 1, At, B1); PG8_BAR; PG8_SCHED;
;             PG8_LDB(B0, 1, 0); PG8_LDB(B1, 1, 1); PG8_SCHED; PG8_LDA(At, 1, 0); PG8_STAGE(PG8_SA(0, 1), a2 + hstep, voffA);
;             PG8_WAIT_V(8); PG8_WAIT_L(0); PG8_BAR; PG8_MMA(0, 0, At, B0); PG8_MMA(0, 1, At, B1); PG8_BAR; PG8_SCHED;
	s_setprio 1
	s_waitcnt lgkmcnt(0)
	v_mfma_f32_16x16x32_bf16 v[62:65], v[130:133], v[162:165], v[62:65]
	v_mfma_f32_16x16x32_bf16 v[58:61], v[138:141], v[162:165], v[58:61]
	v_mfma_f32_16x16x32_bf16 v[46:49], v[130:133], v[170:173], v[46:49]
	v_mfma_f32_16x16x32_bf16 v[42:45], v[138:141], v[170:173], v[42:45]
	v_mfma_f32_16x16x32_bf16 v[28:31], v[130:133], v[188:191], v[28:31]
	v_mfma_f32_16x16x32_bf16 v[24:27], v[138:141], v[188:191], v[24:27]
	v_mfma_f32_16x16x32_bf16 v[12:15], v[130:133], v[214:217], v[12:15]
	v_mfma_f32_16x16x32_bf16 v[8:11], v[138:141], v[214:217], v[8:11]
	v_mfma_f32_16x16x32_bf16 v[62:65], v[134:137], v[166:169], v[62:65]
	v_mfma_f32_16x16x32_bf16 v[58:61], v[142:145], v[166:169], v[58:61]
	v_mfma_f32_16x16x32_bf16 v[46:49], v[134:137], v[174:177], v[46:49]
	v_mfma_f32_16x16x32_bf16 v[42:45], v[142:145], v[174:177], v[42:45]
	v_mfma_f32_16x16x32_bf16 v[28:31], v[134:137], v[204:207], v[28:31]
	v_mfma_f32_16x16x32_bf16 v[24:27], v[142:145], v[204:207], v[24:27]
	v_mfma_f32_16x16x32_bf16 v[12:15], v[134:137], v[218:221], v[12:15]
	v_mfma_f32_16x16x32_bf16 v[8:11], v[142:145], v[218:221], v[8:11]
	v_mfma_f32_16x16x32_bf16 v[54:57], v[146:149], v[162:165], v[54:57]
	v_mfma_f32_16x16x32_bf16 v[50:53], v[154:157], v[162:165], v[50:53]
	v_mfma_f32_16x16x32_bf16 v[38:41], v[146:149], v[170:173], v[38:41]
	v_mfma_f32_16x16x32_bf16 v[34:37], v[154:157], v[170:173], v[34:37]
	v_mfma_f32_16x16x32_bf16 v[20:23], v[146:149], v[188:191], v[20:23]
	v_mfma_f32_16x16x32_bf16 v[16:19], v[154:157], v[188:191], v[16:19]
	v_mfma_f32_16x16x32_bf16 v[4:7], v[146:149], v[214:217], v[4:7]
	v_mfma_f32_16x16x32_bf16 v[0:3], v[154:157], v[214:217], v[0:3]
	v_mfma_f32_16x16x32_bf16 v[54:57], v[150:153], v[166:169], v[54:57]
	v_mfma_f32_16x16x32_bf16 v[50:53], v[158:161], v[166:169], v[50:53]
	v_mfma_f32_16x16x32_bf16 v[38:41], v[150:153], v[174:177], v[38:41]
	v_mfma_f32_16x16x32_bf16 v[34:37], v[158:161], v[174:177], v[34:37]
	v_mfma_f32_16x16x32_bf16 v[20:23], v[150:153], v[204:207], v[20:23]
	v_mfma_f32_16x16x32_bf16 v[16:19], v[158:161], v[204:207], v[16:19]
	v_mfma_f32_16x16x32_bf16 v[4:7], v[150:153], v[218:221], v[4:7]
	v_mfma_f32_16x16x32_bf16 v[0:3], v[158:161], v[218:221], v[0:3]
	s_setprio 0
	s_barrier
	s_add_i32 s51, 0, 0x18000
	s_add_i32 s53, 0, 0x1c000
	v_add_u32_e32 v142, s51, v211
	v_add_u32_e32 v158, s53, v211
	ds_read_b128 v[130:133], v142
	ds_read_b128 v[134:137], v142 offset:1024
	ds_read_b128 v[138:141], v142 offset:2048
	ds_read_b128 v[142:145], v142 offset:3072
	ds_read_b128 v[146:149], v158
	ds_read_b128 v[150:153], v158 offset:1024
	ds_read_b128 v[154:157], v158 offset:2048
	ds_read_b128 v[158:161], v158 offset:3072
	s_add_u32 s2, s28, 0xb0000
	s_addc_u32 s3, s29, 0
	s_mov_b32 m0, s39
	v_lshl_add_u64 v[226:227], s[2:3], 0, v[182:183]
	ds_read_b128 v[162:165], v213 offset:32768
	ds_read_b128 v[166:169], v213 offset:33792
	ds_read_b128 v[170:173], v213 offset:34816
	ds_read_b128 v[174:177], v213 offset:35840
	ds_read_b128 v[188:191], v213 offset:36864
	ds_read_b128 v[204:207], v213 offset:37888
	ds_read_b128 v[214:217], v213 offset:38912
	ds_read_b128 v[218:221], v213 offset:39936
	global_load_lds_dwordx4 v[226:227], off
	v_lshl_add_u64 v[226:227], s[2:3], 0, v[180:181]
	s_mov_b32 m0, s40
	s_nop 0
	global_load_lds_dwordx4 v[226:227], off
	s_waitcnt vmcnt(8)
	s_waitcnt lgkmcnt(0)
	s_barrier
	s_setprio 1
	s_waitcnt lgkmcnt(0)
	v_mfma_f32_16x16x32_bf16 v[126:129], v[130:133], v[162:165], v[126:129]
	v_mfma_f32_16x16x32_bf16 v[122:125], v[138:141], v[162:165], v[122:125]
	v_mfma_f32_16x16x32_bf16 v[110:113], v[130:133], v[170:173], v[110:113]
	v_mfma_f32_16x16x32_bf16 v[106:109], v[138:141], v[170:173], v[106:109]
	v_mfma_f32_16x16x32_bf16 v[94:97], v[130:133], v[188:191], v[94:97]
	v_mfma_f32_16x16x32_bf16 v[90:93], v[138:141], v[188:191], v[90:93]
	v_mfma_f32_16x16x32_bf16 v[78:81], v[130:133], v[214:217], v[78:81]
	v_mfma_f32_16x16x32_bf16 v[74:77], v[138:141], v[214:217], v[74:77]
	v_mfma_f32_16x16x32_bf16 v[126:129], v[134:137], v[166:169], v[126:129]
	v_mfma_f32_16x16x32_bf16 v[122:125], v[142:145], v[166:169], v[122:125]
	v_mfma_f32_16x16x32_bf16 v[110:113], v[134:137], v[174:177], v[110:113]
	v_mfma_f32_16x16x32_bf16 v[106:109], v[142:145], v[174:177], v[106:109]
	v_mfma_f32_16x16x32_bf16 v[94:97], v[134:137], v[204:207], v[94:97]
	v_mfma_f32_16x16x32_bf16 v[90:93], v[142:145], v[204:207], v[90:93]
	v_mfma_f32_16x16x32_bf16 v[78:81], v[134:137], v[218:221], v[78:81]
	v_mfma_f32_16x16x32_bf16 v[74:77], v[142:145], v[218:221], v[74:77]
	v_mfma_f32_16x16x32_bf16 v[118:121], v[146:149], v[162:165], v[118:121]
	v_mfma_f32_16x16x32_bf16 v[114:117], v[154:157], v[162:165], v[114:117]
	v_mfma_f32_16x16x32_bf16 v[102:105], v[146:149], v[170:173], v[102:105]
	v_mfma_f32_16x16x32_bf16 v[98:101], v[154:157], v[170:173], v[98:101]
	v_mfma_f32_16x16x32_bf16 v[86:89], v[146:149], v[188:191], v[86:89]
	v_mfma_f32_16x16x32_bf16 v[82:85], v[154:157], v[188:191], v[82:85]
	v_mfma_f32_16x16x32_bf16 v[70:73], v[146:149], v[214:217], v[70:73]
	v_mfma_f32_16x16x32_bf16 v[66:69], v[154:157], v[214:217], v[66:69]
	v_mfma_f32_16x16x32_bf16 v[118:121], v[150:153], v[166:169], v[118:121]
	v_mfma_f32_16x16x32_bf16 v[114:117], v[158:161], v[166:169], v[114:117]
	v_mfma_f32_16x16x32_bf16 v[102:105], v[150:153], v[174:177], v[102:105]
	v_mfma_f32_16x16x32_bf16 v[98:101], v[158:161], v[174:177], v[98:101]
	v_mfma_f32_16x16x32_bf16 v[86:89], v[150:153], v[204:207], v[86:89]
	v_mfma_f32_16x16x32_bf16 v[82:85], v[158:161], v[204:207], v[82:85]
	v_mfma_f32_16x16x32_bf16 v[70:73], v[150:153], v[218:221], v[70:73]
	v_mfma_f32_16x16x32_bf16 v[66:69], v[158:161], v[218:221], v[66:69]
	s_setprio 0
	s_barrier
; #define PG8_STAGE(bufoff, gbase, voff) do { _Pragma("unroll") for (int _i = 0; _i < 2; ++_i) \
;         __builtin_amdgcn_global_load_lds((const unsigned*)((const char*)(gbase) + (voff)[_i]), (PG8_LAS unsigned*)(lds + (bufoff) + ldsw + _i * 8192), 16, 0, 0); } while (0)
; #define PG8_LDA(dst, b, h) do { _Pragma("unroll") for (int m = 0; m < 4; ++m) _Pragma("unroll") for (int k = 0; k < 2; ++k) dst[m][k] = *(const PG8_LAS bf16x8*)(lds + PG8_SA(b, h) + aoff + m * 2048 + k * 1024); } while (0)
; #define PG8_MMA(ai, bj, At, Bt) do { __builtin_amdgcn_s_setprio(1); _Pragma("unroll") for (int m = 0; m < 4; ++m) _Pragma("unroll") for (int n = 0; n < 2; ++n) _Pragma("unroll") for (int k = 0; k < 2; ++k) \
;         acc[ai][bj][m][n] = __builtin_amdgcn_mfma_f32_16x16x32_bf16(Bt[n][k], At[m][k], acc[ai][bj][m][n], 0, 0, 0); __builtin_amdgcn_s_setprio(0); } while (0)
; #define PG8_WAIT_V(n) asm volatile("s_waitcnt vmcnt(" #n ")" ::: "memory")
; #define PG8_WAIT_L(n) asm volatile("s_waitcnt lgkmcnt(" #n ")" ::: "memory")
; #define PG8_BAR __builtin_amdgcn_s_barrier()
; #define PG8_SCHED __builtin_amdgcn_sched_barrier(0)
; template <class Epi, class Sched, bool ALIGN_EPI = false, bool SP2 = false>
; __device__ __forceinline__ void gemm_phase(PG8_LAS unsigned char* lds, const Gemm g, const Sched& S, const Epi& E, int tid_in) {
;     ...
;             PG8_LDA(At, 1, 1); PG8_STAGE(PG8_SB(1, 0), b3, voffB); PG8_STAGE(PG8_SB(1, 1), b3 + hstep, voffB); PG8_STAGE(PG8_SA(1, 0), a3, voffA);
;             PG8_WAIT_V(8); PG8_WAIT_L(0); PG8_BAR; PG8_MMA(1, 0, At, B0); PG8_MMA(1, 1, At, B1); PG8_BAR; PG8_SCHED;
;     ...
;         if constexpr (ALIGN_EPI) { if (wr == 0) PG8_BAR; }
	s_add_i32 s2, s51, s36
	v_lshl_add_u64 v[192:193], v[192:193], 0, s[84:85]
	s_mov_b32 m0, s2
	ds_read_b128 v[162:165], v213 offset:49152
	ds_read_b128 v[166:169], v213 offset:50176
	ds_read_b128 v[170:173], v213 offset:51200
	ds_read_b128 v[174:177], v213 offset:52224
	ds_read_b128 v[188:191], v213 offset:53248
	ds_read_b128 v[204:207], v213 offset:54272
	ds_read_b128 v[214:217], v213 offset:55296
	ds_read_b128 v[218:221], v213 offset:56320
	global_load_lds_dwordx4 v[192:193], off
	s_add_i32 m0, s2, 0x2000
	s_add_u32 s2, s26, 0xb0080
	v_lshl_add_u64 v[192:193], v[208:209], 0, s[84:85]
	s_addc_u32 s3, s27, 0
	s_add_i32 s26, s53, s36
	global_load_lds_dwordx4 v[192:193], off
	v_lshl_add_u64 v[192:193], s[2:3], 0, v[32:33]
	s_mov_b32 m0, s26
	s_nop 0
	global_load_lds_dwordx4 v[192:193], off
	v_lshl_add_u64 v[192:193], s[2:3], 0, v[178:179]
	s_add_i32 m0, s26, 0x2000
	s_nop 0
	global_load_lds_dwordx4 v[192:193], off
	v_lshl_add_u64 v[192:193], v[222:223], 0, s[84:85]
	s_mov_b32 m0, s41
	s_nop 0
	global_load_lds_dwordx4 v[192:193], off
	v_lshl_add_u64 v[192:193], v[224:225], 0, s[84:85]
	s_mov_b32 m0, s42
	s_nop 0
	global_load_lds_dwordx4 v[192:193], off
	s_waitcnt vmcnt(8)
	s_waitcnt lgkmcnt(0)
	s_barrier
	s_setprio 1
	s_waitcnt lgkmcnt(0)
	v_mfma_f32_16x16x32_bf16 v[62:65], v[130:133], v[162:165], v[62:65]
	v_mfma_f32_16x16x32_bf16 v[58:61], v[138:141], v[162:165], v[58:61]
	v_mfma_f32_16x16x32_bf16 v[46:49], v[130:133], v[170:173], v[46:49]
	v_mfma_f32_16x16x32_bf16 v[42:45], v[138:141], v[170:173], v[42:45]
	v_mfma_f32_16x16x32_bf16 v[28:31], v[130:133], v[188:191], v[28:31]
	v_mfma_f32_16x16x32_bf16 v[24:27], v[138:141], v[188:191], v[24:27]
	v_mfma_f32_16x16x32_bf16 v[12:15], v[130:133], v[214:217], v[12:15]
	v_mfma_f32_16x16x32_bf16 v[8:11], v[138:141], v[214:217], v[8:11]
	v_mfma_f32_16x16x32_bf16 v[62:65], v[134:137], v[166:169], v[62:65]
	v_mfma_f32_16x16x32_bf16 v[58:61], v[142:145], v[166:169], v[58:61]
	v_mfma_f32_16x16x32_bf16 v[46:49], v[134:137], v[174:177], v[46:49]
	v_mfma_f32_16x16x32_bf16 v[42:45], v[142:145], v[174:177], v[42:45]
	v_mfma_f32_16x16x32_bf16 v[28:31], v[134:137], v[204:207], v[28:31]
	v_mfma_f32_16x16x32_bf16 v[24:27], v[142:145], v[204:207], v[24:27]
	v_mfma_f32_16x16x32_bf16 v[12:15], v[134:137], v[218:221], v[12:15]
	v_mfma_f32_16x16x32_bf16 v[8:11], v[142:145], v[218:221], v[8:11]
	v_mfma_f32_16x16x32_bf16 v[54:57], v[146:149], v[162:165], v[54:57]
	v_mfma_f32_16x16x32_bf16 v[50:53], v[154:157], v[162:165], v[50:53]
	v_mfma_f32_16x16x32_bf16 v[38:41], v[146:149], v[170:173], v[38:41]
	v_mfma_f32_16x16x32_bf16 v[34:37], v[154:157], v[170:173], v[34:37]
	v_mfma_f32_16x16x32_bf16 v[20:23], v[146:149], v[188:191], v[20:23]
	v_mfma_f32_16x16x32_bf16 v[16:19], v[154:157], v[188:191], v[16:19]
	v_mfma_f32_16x16x32_bf16 v[4:7], v[146:149], v[214:217], v[4:7]
	v_mfma_f32_16x16x32_bf16 v[0:3], v[154:157], v[214:217], v[0:3]
	v_mfma_f32_16x16x32_bf16 v[54:57], v[150:153], v[166:169], v[54:57]
	v_mfma_f32_16x16x32_bf16 v[50:53], v[158:161], v[166:169], v[50:53]
	v_mfma_f32_16x16x32_bf16 v[38:41], v[150:153], v[174:177], v[38:41]
	v_mfma_f32_16x16x32_bf16 v[34:37], v[158:161], v[174:177], v[34:37]
	v_mfma_f32_16x16x32_bf16 v[20:23], v[150:153], v[204:207], v[20:23]
	v_mfma_f32_16x16x32_bf16 v[16:19], v[158:161], v[204:207], v[16:19]
	v_mfma_f32_16x16x32_bf16 v[4:7], v[150:153], v[218:221], v[4:7]
	v_mfma_f32_16x16x32_bf16 v[0:3], v[158:161], v[218:221], v[0:3]
	s_setprio 0
	s_barrier
	s_add_i32 s50, s50, 2
	s_add_u32 s48, s48, 0x100
	s_addc_u32 s49, s49, 0
	s_cmp_gt_u32 s50, 41
	s_mov_b64 s[2:3], s[24:25]
	s_cbranch_scc0 .LBB0_340
	s_and_b64 vcc, exec, s[20:21]
	s_cbranch_vccz .LBB0_343
	s_barrier

; #define PG8_STAGE(bufoff, gbase, voff) do { _Pragma("unroll") for (int _i = 0; _i < 2; ++_i) \
;         __builtin_amdgcn_global_load_lds((const unsigned*)((const char*)(gbase) + (voff)[_i]), (PG8_LAS unsigned*)(lds + (bufoff) + ldsw + _i * 8192), 16, 0, 0); } while (0)
; #define PG8_LDA(dst, b, h) do { _Pragma("unroll") for (int m = 0; m < 4; ++m) _Pragma("unroll") for (int k = 0; k < 2; ++k) dst[m][k] = *(const PG8_LAS bf16x8*)(lds + PG8_SA(b, h) + aoff + m * 2048 + k * 1024); } while (0)
; #define PG8_LDB(dst, b, h) do { _Pragma("unroll") for (int n = 0; n < 2; ++n) _Pragma("unroll") for (int k = 0; k < 2; ++k) dst[n][k] = *(const PG8_LAS bf16x8*)(lds + PG8_SB(b, h) + boff + n * 2048 + k * 1024); } while (0)
; #define PG8_MMA(ai, bj, At, Bt) do { __builtin_amdgcn_s_setprio(1); _Pragma("unroll") for (int m = 0; m < 4; ++m) _Pragma("unroll") for (int n = 0; n < 2; ++n) _Pragma("unroll") for (int k = 0; k < 2; ++k) \
;         acc[ai][bj][m][n] = __builtin_amdgcn_mfma_f32_16x16x32_bf16(Bt[n][k], At[m][k], acc[ai][bj][m][n], 0, 0, 0); __builtin_amdgcn_s_setprio(0); } while (0)
; #define PG8_WAIT_V(n) asm volatile("s_waitcnt vmcnt(" #n ")" ::: "memory")
; #define PG8_WAIT_L(n) asm volatile("s_waitcnt lgkmcnt(" #n ")" ::: "memory")
; #define PG8_BAR __builtin_amdgcn_s_barrier()
; #define PG8_SCHED __builtin_amdgcn_sched_barrier(0)
; template <class Epi, class Sched, bool ALIGN_EPI = false, bool SP2 = false>
; __device__ __forceinline__ void gemm_phase(PG8_LAS unsigned char* lds, const Gemm g, const Sched& S, const Epi& E, int tid_in) {
;     ...
;             const bool last = (t == nt - 2);
;             const char* a1 = cA + (size_t)(t + 1) * kstep;
;             const char* a2 = last ? nA : cA + (size_t)(t + 2) * kstep; const char* b2 = last ? nB : cB + (size_t)(t + 2) * kstep;
;             const char* a3 = a2 + kstep; const char* b3 = b2 + kstep;
;             if (last && has_next) S.a_ready(nxt);
;             if constexpr (SP2) {
;             PG8_LDB(B0, 0, 0); PG8_LDB(B1, 0, 1); PG8_SCHED; PG8_LDA(At, 0, 0); PG8_STAGE(PG8_SA(1, 1), a1 + hstep, voffA);
;             PG8_WAIT_V(8); PG8_WAIT_L(0); PG8_BAR; PG8_MMA(0, 0, At, B0); PG8_MMA(0, 1, At, B1); PG8_BAR; PG8_SCHED;
;             PG8_LDA(At, 0, 1); PG8_STAGE(PG8_SB(0, 0), b2, voffB); PG8_STAGE(PG8_SB(0, 1), b2 + hstep, voffB); PG8_STAGE(PG8_SA(0, 0), a2, voffA);
.LBB0_388:
	s_add_u32 s20, s6, 0xfffc0080
	s_addc_u32 s21, s7, -1
	s_add_i32 s45, 0, 0x10000
	s_cmp_eq_u32 s44, 12
	s_cselect_b32 s23, s15, s21
	s_cselect_b32 s22, s40, s20
	s_cselect_b32 s21, s13, s43
	s_cselect_b32 s20, s41, s42
	s_add_i32 s48, 0, 0x14000
	v_add_u32_e32 v156, s45, v149
	v_add_u32_e32 v172, s48, v149
	ds_read_b128 v[140:143], v156
	ds_read_b128 v[144:147], v156 offset:1024
	ds_read_b128 v[152:155], v156 offset:2048
	ds_read_b128 v[156:159], v156 offset:3072
	ds_read_b128 v[160:163], v172
	ds_read_b128 v[164:167], v172 offset:1024
	ds_read_b128 v[168:171], v172 offset:2048
	ds_read_b128 v[172:175], v172 offset:3072
	v_lshl_add_u64 v[192:193], s[6:7], 0, v[136:137]
	s_add_i32 m0, s29, 0xc000
	ds_read_b128 v[176:179], v151
	ds_read_b128 v[180:183], v151 offset:1024
	ds_read_b128 v[184:187], v151 offset:2048
	ds_read_b128 v[188:191], v151 offset:3072
	ds_read_b128 v[204:207], v151 offset:4096
	ds_read_b128 v[208:211], v151 offset:5120
	ds_read_b128 v[212:215], v151 offset:6144
	ds_read_b128 v[216:219], v151 offset:7168
	global_load_lds_dwordx4 v[192:193], off
	v_lshl_add_u64 v[192:193], s[6:7], 0, v[138:139]
	s_add_i32 m0, s29, 0xe000
	s_nop 0
	global_load_lds_dwordx4 v[192:193], off
	s_waitcnt vmcnt(8)
	s_waitcnt lgkmcnt(0)
	s_barrier
	s_setprio 1
	s_waitcnt lgkmcnt(0)
	v_mfma_f32_16x16x32_bf16 v[126:129], v[140:143], v[176:179], v[126:129]
	v_mfma_f32_16x16x32_bf16 v[122:125], v[152:155], v[176:179], v[122:125]
	v_mfma_f32_16x16x32_bf16 v[110:113], v[140:143], v[184:187], v[110:113]
	v_mfma_f32_16x16x32_bf16 v[106:109], v[152:155], v[184:187], v[106:109]
	v_mfma_f32_16x16x32_bf16 v[94:97], v[140:143], v[204:207], v[94:97]
	v_mfma_f32_16x16x32_bf16 v[90:93], v[152:155], v[204:207], v[90:93]
	v_mfma_f32_16x16x32_bf16 v[78:81], v[140:143], v[212:215], v[78:81]
	v_mfma_f32_16x16x32_bf16 v[74:77], v[152:155], v[212:215], v[74:77]
	v_mfma_f32_16x16x32_bf16 v[126:129], v[144:147], v[180:183], v[126:129]
	v_mfma_f32_16x16x32_bf16 v[122:125], v[156:159], v[180:183], v[122:125]
	v_mfma_f32_16x16x32_bf16 v[110:113], v[144:147], v[188:191], v[110:113]
	v_mfma_f32_16x16x32_bf16 v[106:109], v[156:159], v[188:191], v[106:109]
	v_mfma_f32_16x16x32_bf16 v[94:97], v[144:147], v[208:211], v[94:97]
	v_mfma_f32_16x16x32_bf16 v[90:93], v[156:159], v[208:211], v[90:93]
	v_mfma_f32_16x16x32_bf16 v[78:81], v[144:147], v[216:219], v[78:81]
	v_mfma_f32_16x16x32_bf16 v[74:77], v[156:159], v[216:219], v[74:77]
	v_mfma_f32_16x16x32_bf16 v[118:121], v[160:163], v[176:179], v[118:121]
	v_mfma_f32_16x16x32_bf16 v[114:117], v[168:171], v[176:179], v[114:117]
	v_mfma_f32_16x16x32_bf16 v[102:105], v[160:163], v[184:187], v[102:105]
	v_mfma_f32_16x16x32_bf16 v[98:101], v[168:171], v[184:187], v[98:101]
	v_mfma_f32_16x16x32_bf16 v[86:89], v[160:163], v[204:207], v[86:89]
	v_mfma_f32_16x16x32_bf16 v[82:85], v[168:171], v[204:207], v[82:85]
	v_mfma_f32_16x16x32_bf16 v[70:73], v[160:163], v[212:215], v[70:73]
	v_mfma_f32_16x16x32_bf16 v[66:69], v[168:171], v[212:215], v[66:69]
	v_mfma_f32_16x16x32_bf16 v[118:121], v[164:167], v[180:183], v[118:121]
	v_mfma_f32_16x16x32_bf16 v[114:117], v[172:175], v[180:183], v[114:117]
	v_mfma_f32_16x16x32_bf16 v[102:105], v[164:167], v[188:191], v[102:105]
	v_mfma_f32_16x16x32_bf16 v[98:101], v[172:175], v[188:191], v[98:101]
	v_mfma_f32_16x16x32_bf16 v[86:89], v[164:167], v[208:211], v[86:89]
	v_mfma_f32_16x16x32_bf16 v[82:85], v[172:175], v[208:211], v[82:85]
	v_mfma_f32_16x16x32_bf16 v[70:73], v[164:167], v[216:219], v[70:73]
	v_mfma_f32_16x16x32_bf16 v[66:69], v[172:175], v[216:219], v[66:69]
	s_setprio 0
	s_barrier
	s_add_i32 s45, s45, s28
	v_lshl_add_u64 v[192:193], s[20:21], 0, v[32:33]
	s_mov_b32 m0, s45
	ds_read_b128 v[176:179], v151 offset:16384
	ds_read_b128 v[180:183], v151 offset:17408
	ds_read_b128 v[184:187], v151 offset:18432
	ds_read_b128 v[188:191], v151 offset:19456
	ds_read_b128 v[204:207], v151 offset:20480
	ds_read_b128 v[208:211], v151 offset:21504
	ds_read_b128 v[212:215], v151 offset:22528
	ds_read_b128 v[216:219], v151 offset:23552
	global_load_lds_dwordx4 v[192:193], off
	s_add_i32 m0, s45, 0x2000
	s_add_u32 s46, s20, 0x40000
	v_lshl_add_u64 v[220:221], s[20:21], 0, v[130:131]
	s_addc_u32 s47, s21, 0
	s_add_i32 s45, s48, s28
	global_load_lds_dwordx4 v[220:221], off
	v_lshl_add_u64 v[222:223], s[46:47], 0, v[32:33]
	s_mov_b32 m0, s45
	v_lshl_add_u64 v[224:225], s[22:23], 0, v[132:133]
	global_load_lds_dwordx4 v[222:223], off
	v_lshl_add_u64 v[222:223], s[46:47], 0, v[130:131]
	s_add_i32 m0, s45, 0x2000
	s_nop 0
	global_load_lds_dwordx4 v[222:223], off
	v_lshl_add_u64 v[222:223], s[22:23], 0, v[134:135]
	s_mov_b32 m0, s29
	s_nop 0
	global_load_lds_dwordx4 v[222:223], off
	s_mov_b32 m0, s30
	s_nop 0
	global_load_lds_dwordx4 v[224:225], off
	s_waitcnt vmcnt(8)
	s_waitcnt lgkmcnt(0)
	s_barrier
; #define PG8_STAGE(bufoff, gbase, voff) do { _Pragma("unroll") for (int _i = 0; _i < 2; ++_i) \
;         __builtin_amdgcn_global_load_lds((const unsigned*)((const char*)(gbase) + (voff)[_i]), (PG8_LAS unsigned*)(lds + (bufoff) + ldsw + _i * 8192), 16, 0, 0); } while (0)
; #define PG8_LDA(dst, b, h) do { _Pragma("unroll") for (int m = 0; m < 4; ++m) _Pragma("unroll") for (int k = 0; k < 2; ++k) dst[m][k] = *(const PG8_LAS bf16x8*)(lds + PG8_SA(b, h) + aoff + m * 2048 + k * 1024); } while (0)
; #define PG8_LDB(dst, b, h) do { _Pragma("unroll") for (int n = 0; n < 2; ++n) _Pragma("unroll") for (int k = 0; k < 2; ++k) dst[n][k] = *(const PG8_LAS bf16x8*)(lds + PG8_SB(b, h) + boff + n * 2048 + k * 1024); } while (0)
; #define PG8_MMA(ai, bj, At, Bt) do { __builtin_amdgcn_s_setprio(1); _Pragma("unroll") for (int m = 0; m < 4; ++m) _Pragma("unroll") for (int n = 0; n < 2; ++n) _Pragma("unroll") for (int k = 0; k < 2; ++k) \
;         acc[ai][bj][m][n] = __builtin_amdgcn_mfma_f32_16x16x32_bf16(Bt[n][k], At[m][k], acc[ai][bj][m][n], 0, 0, 0); __builtin_amdgcn_s_setprio(0); } while (0)
; #define PG8_WAIT_V(n) asm volatile("s_waitcnt vmcnt(" #n ")" ::: "memory")
; #define PG8_WAIT_L(n) asm volatile("s_waitcnt lgkmcnt(" #n ")" ::: "memory")
; #define PG8_BAR __builtin_amdgcn_s_barrier()
; #define PG8_SCHED __builtin_amdgcn_sched_barrier(0)
; template <class Epi, class Sched, bool ALIGN_EPI = false, bool SP2 = false>
; __device__ __forceinline__ void gemm_phase(PG8_LAS unsigned char* lds, const Gemm g, const Sched& S, const Epi& E, int tid_in) {
;     ...
;             PG8_WAIT_V(8); PG8_WAIT_L(0); PG8_BAR; PG8_MMA(1, 0, At, B0); PG8_MMA(1, 1, At, B1); PG8_BAR; PG8_SCHED;
;             PG8_LDB(B0, 1, 0); PG8_LDB(B1, 1, 1); PG8_SCHED; PG8_LDA(At, 1, 0); PG8_STAGE(PG8_SA(0, 1), a2 + hstep, voffA);
;             PG8_WAIT_V(8); PG8_WAIT_L(0); PG8_BAR; PG8_MMA(0, 0, At, B0); PG8_MMA(0, 1, At, B1); PG8_BAR; PG8_SCHED;
	s_setprio 1
	s_waitcnt lgkmcnt(0)
	v_mfma_f32_16x16x32_bf16 v[62:65], v[140:143], v[176:179], v[62:65]
	v_mfma_f32_16x16x32_bf16 v[58:61], v[152:155], v[176:179], v[58:61]
	v_mfma_f32_16x16x32_bf16 v[46:49], v[140:143], v[184:187], v[46:49]
	v_mfma_f32_16x16x32_bf16 v[42:45], v[152:155], v[184:187], v[42:45]
	v_mfma_f32_16x16x32_bf16 v[28:31], v[140:143], v[204:207], v[28:31]
	v_mfma_f32_16x16x32_bf16 v[24:27], v[152:155], v[204:207], v[24:27]
	v_mfma_f32_16x16x32_bf16 v[12:15], v[140:143], v[212:215], v[12:15]
	v_mfma_f32_16x16x32_bf16 v[8:11], v[152:155], v[212:215], v[8:11]
	v_mfma_f32_16x16x32_bf16 v[62:65], v[144:147], v[180:183], v[62:65]
	v_mfma_f32_16x16x32_bf16 v[58:61], v[156:159], v[180:183], v[58:61]
	v_mfma_f32_16x16x32_bf16 v[46:49], v[144:147], v[188:191], v[46:49]
	v_mfma_f32_16x16x32_bf16 v[42:45], v[156:159], v[188:191], v[42:45]
	v_mfma_f32_16x16x32_bf16 v[28:31], v[144:147], v[208:211], v[28:31]
	v_mfma_f32_16x16x32_bf16 v[24:27], v[156:159], v[208:211], v[24:27]
	v_mfma_f32_16x16x32_bf16 v[12:15], v[144:147], v[216:219], v[12:15]
	v_mfma_f32_16x16x32_bf16 v[8:11], v[156:159], v[216:219], v[8:11]
	v_mfma_f32_16x16x32_bf16 v[54:57], v[160:163], v[176:179], v[54:57]
	v_mfma_f32_16x16x32_bf16 v[50:53], v[168:171], v[176:179], v[50:53]
	v_mfma_f32_16x16x32_bf16 v[38:41], v[160:163], v[184:187], v[38:41]
	v_mfma_f32_16x16x32_bf16 v[34:37], v[168:171], v[184:187], v[34:37]
	v_mfma_f32_16x16x32_bf16 v[20:23], v[160:163], v[204:207], v[20:23]
	v_mfma_f32_16x16x32_bf16 v[16:19], v[168:171], v[204:207], v[16:19]
	v_mfma_f32_16x16x32_bf16 v[4:7], v[160:163], v[212:215], v[4:7]
	v_mfma_f32_16x16x32_bf16 v[0:3], v[168:171], v[212:215], v[0:3]
	v_mfma_f32_16x16x32_bf16 v[54:57], v[164:167], v[180:183], v[54:57]
	v_mfma_f32_16x16x32_bf16 v[50:53], v[172:175], v[180:183], v[50:53]
	v_mfma_f32_16x16x32_bf16 v[38:41], v[164:167], v[188:191], v[38:41]
	v_mfma_f32_16x16x32_bf16 v[34:37], v[172:175], v[188:191], v[34:37]
	v_mfma_f32_16x16x32_bf16 v[20:23], v[164:167], v[208:211], v[20:23]
	v_mfma_f32_16x16x32_bf16 v[16:19], v[172:175], v[208:211], v[16:19]
	v_mfma_f32_16x16x32_bf16 v[4:7], v[164:167], v[216:219], v[4:7]
	v_mfma_f32_16x16x32_bf16 v[0:3], v[172:175], v[216:219], v[0:3]
	s_setprio 0
	s_barrier
	s_add_i32 s45, 0, 0x18000
	s_add_i32 s46, 0, 0x1c000
	v_add_u32_e32 v156, s45, v149
	v_add_u32_e32 v172, s46, v149
	ds_read_b128 v[140:143], v156
	ds_read_b128 v[144:147], v156 offset:1024
	ds_read_b128 v[152:155], v156 offset:2048
	ds_read_b128 v[156:159], v156 offset:3072
	ds_read_b128 v[160:163], v172
	ds_read_b128 v[164:167], v172 offset:1024
	ds_read_b128 v[168:171], v172 offset:2048
	ds_read_b128 v[172:175], v172 offset:3072
	s_add_u32 s22, s22, 0x40000
	s_addc_u32 s23, s23, 0
	s_mov_b32 m0, s31
	v_lshl_add_u64 v[226:227], s[22:23], 0, v[134:135]
	ds_read_b128 v[176:179], v151 offset:32768
	ds_read_b128 v[180:183], v151 offset:33792
	ds_read_b128 v[184:187], v151 offset:34816
	ds_read_b128 v[188:191], v151 offset:35840
	ds_read_b128 v[204:207], v151 offset:36864
	ds_read_b128 v[208:211], v151 offset:37888
	ds_read_b128 v[212:215], v151 offset:38912
	ds_read_b128 v[216:219], v151 offset:39936
	global_load_lds_dwordx4 v[226:227], off
	v_lshl_add_u64 v[226:227], s[22:23], 0, v[132:133]
	s_mov_b32 m0, s34
	s_nop 0
	global_load_lds_dwordx4 v[226:227], off
	s_waitcnt vmcnt(8)
	s_waitcnt lgkmcnt(0)
	s_barrier
	s_setprio 1
	s_waitcnt lgkmcnt(0)
	v_mfma_f32_16x16x32_bf16 v[126:129], v[140:143], v[176:179], v[126:129]
	v_mfma_f32_16x16x32_bf16 v[122:125], v[152:155], v[176:179], v[122:125]
	v_mfma_f32_16x16x32_bf16 v[110:113], v[140:143], v[184:187], v[110:113]
	v_mfma_f32_16x16x32_bf16 v[106:109], v[152:155], v[184:187], v[106:109]
	v_mfma_f32_16x16x32_bf16 v[94:97], v[140:143], v[204:207], v[94:97]
	v_mfma_f32_16x16x32_bf16 v[90:93], v[152:155], v[204:207], v[90:93]
	v_mfma_f32_16x16x32_bf16 v[78:81], v[140:143], v[212:215], v[78:81]
	v_mfma_f32_16x16x32_bf16 v[74:77], v[152:155], v[212:215], v[74:77]
	v_mfma_f32_16x16x32_bf16 v[126:129], v[144:147], v[180:183], v[126:129]
	v_mfma_f32_16x16x32_bf16 v[122:125], v[156:159], v[180:183], v[122:125]
	v_mfma_f32_16x16x32_bf16 v[110:113], v[144:147], v[188:191], v[110:113]
	v_mfma_f32_16x16x32_bf16 v[106:109], v[156:159], v[188:191], v[106:109]
	v_mfma_f32_16x16x32_bf16 v[94:97], v[144:147], v[208:211], v[94:97]
	v_mfma_f32_16x16x32_bf16 v[90:93], v[156:159], v[208:211], v[90:93]
	v_mfma_f32_16x16x32_bf16 v[78:81], v[144:147], v[216:219], v[78:81]
	v_mfma_f32_16x16x32_bf16 v[74:77], v[156:159], v[216:219], v[74:77]
	v_mfma_f32_16x16x32_bf16 v[118:121], v[160:163], v[176:179], v[118:121]
	v_mfma_f32_16x16x32_bf16 v[114:117], v[168:171], v[176:179], v[114:117]
	v_mfma_f32_16x16x32_bf16 v[102:105], v[160:163], v[184:187], v[102:105]
	v_mfma_f32_16x16x32_bf16 v[98:101], v[168:171], v[184:187], v[98:101]
	v_mfma_f32_16x16x32_bf16 v[86:89], v[160:163], v[204:207], v[86:89]
	v_mfma_f32_16x16x32_bf16 v[82:85], v[168:171], v[204:207], v[82:85]
	v_mfma_f32_16x16x32_bf16 v[70:73], v[160:163], v[212:215], v[70:73]
	v_mfma_f32_16x16x32_bf16 v[66:69], v[168:171], v[212:215], v[66:69]
	v_mfma_f32_16x16x32_bf16 v[118:121], v[164:167], v[180:183], v[118:121]
	v_mfma_f32_16x16x32_bf16 v[114:117], v[172:175], v[180:183], v[114:117]
	v_mfma_f32_16x16x32_bf16 v[102:105], v[164:167], v[188:191], v[102:105]
	v_mfma_f32_16x16x32_bf16 v[98:101], v[172:175], v[188:191], v[98:101]
	v_mfma_f32_16x16x32_bf16 v[86:89], v[164:167], v[208:211], v[86:89]
	v_mfma_f32_16x16x32_bf16 v[82:85], v[172:175], v[208:211], v[82:85]
	v_mfma_f32_16x16x32_bf16 v[70:73], v[164:167], v[216:219], v[70:73]
	v_mfma_f32_16x16x32_bf16 v[66:69], v[172:175], v[216:219], v[66:69]
	s_setprio 0
	s_barrier
; #define PG8_STAGE(bufoff, gbase, voff) do { _Pragma("unroll") for (int _i = 0; _i < 2; ++_i) \
;         __builtin_amdgcn_global_load_lds((const unsigned*)((const char*)(gbase) + (voff)[_i]), (PG8_LAS unsigned*)(lds + (bufoff) + ldsw + _i * 8192), 16, 0, 0); } while (0)
; #define PG8_LDA(dst, b, h) do { _Pragma("unroll") for (int m = 0; m < 4; ++m) _Pragma("unroll") for (int k = 0; k < 2; ++k) dst[m][k] = *(const PG8_LAS bf16x8*)(lds + PG8_SA(b, h) + aoff + m * 2048 + k * 1024); } while (0)
; #define PG8_MMA(ai, bj, At, Bt) do { __builtin_amdgcn_s_setprio(1); _Pragma("unroll") for (int m = 0; m < 4; ++m) _Pragma("unroll") for (int n = 0; n < 2; ++n) _Pragma("unroll") for (int k = 0; k < 2; ++k) \
;         acc[ai][bj][m][n] = __builtin_amdgcn_mfma_f32_16x16x32_bf16(Bt[n][k], At[m][k], acc[ai][bj][m][n], 0, 0, 0); __builtin_amdgcn_s_setprio(0); } while (0)
; #define PG8_WAIT_V(n) asm volatile("s_waitcnt vmcnt(" #n ")" ::: "memory")
; #define PG8_WAIT_L(n) asm volatile("s_waitcnt lgkmcnt(" #n ")" ::: "memory")
; #define PG8_BAR __builtin_amdgcn_s_barrier()
; #define PG8_SCHED __builtin_amdgcn_sched_barrier(0)
; template <class Epi, class Sched, bool ALIGN_EPI = false, bool SP2 = false>
; __device__ __forceinline__ void gemm_phase(PG8_LAS unsigned char* lds, const Gemm g, const Sched& S, const Epi& E, int tid_in) {
;     ...
;             PG8_LDA(At, 1, 1); PG8_STAGE(PG8_SB(1, 0), b3, voffB); PG8_STAGE(PG8_SB(1, 1), b3 + hstep, voffB); PG8_STAGE(PG8_SA(1, 0), a3, voffA);
;             PG8_WAIT_V(8); PG8_WAIT_L(0); PG8_BAR; PG8_MMA(1, 0, At, B0); PG8_MMA(1, 1, At, B1); PG8_BAR; PG8_SCHED;
;     ...
;         if constexpr (ALIGN_EPI) { if (wr == 0) PG8_BAR; }
	s_add_i32 s22, s45, s28
	v_lshl_add_u64 v[192:193], v[192:193], 0, s[84:85]
	s_mov_b32 m0, s22
	ds_read_b128 v[176:179], v151 offset:49152
	ds_read_b128 v[180:183], v151 offset:50176
	ds_read_b128 v[184:187], v151 offset:51200
	ds_read_b128 v[188:191], v151 offset:52224
	ds_read_b128 v[204:207], v151 offset:53248
	ds_read_b128 v[208:211], v151 offset:54272
	ds_read_b128 v[212:215], v151 offset:55296
	ds_read_b128 v[216:219], v151 offset:56320
	global_load_lds_dwordx4 v[192:193], off
	s_add_i32 m0, s22, 0x2000
	s_add_u32 s20, s20, 0x40080
	v_lshl_add_u64 v[192:193], v[220:221], 0, s[84:85]
	s_addc_u32 s21, s21, 0
	s_add_i32 s22, s46, s28
	global_load_lds_dwordx4 v[192:193], off
	v_lshl_add_u64 v[192:193], s[20:21], 0, v[32:33]
	s_mov_b32 m0, s22
	s_nop 0
	global_load_lds_dwordx4 v[192:193], off
	v_lshl_add_u64 v[192:193], s[20:21], 0, v[130:131]
	s_add_i32 m0, s22, 0x2000
	s_nop 0
	global_load_lds_dwordx4 v[192:193], off
	v_lshl_add_u64 v[192:193], v[222:223], 0, s[84:85]
	s_mov_b32 m0, s35
	s_nop 0
	global_load_lds_dwordx4 v[192:193], off
	v_lshl_add_u64 v[192:193], v[224:225], 0, s[84:85]
	s_mov_b32 m0, s36
	s_nop 0
	global_load_lds_dwordx4 v[192:193], off
	s_waitcnt vmcnt(8)
	s_waitcnt lgkmcnt(0)
	s_barrier
	s_setprio 1
	s_waitcnt lgkmcnt(0)
	v_mfma_f32_16x16x32_bf16 v[62:65], v[140:143], v[176:179], v[62:65]
	v_mfma_f32_16x16x32_bf16 v[58:61], v[152:155], v[176:179], v[58:61]
	v_mfma_f32_16x16x32_bf16 v[46:49], v[140:143], v[184:187], v[46:49]
	v_mfma_f32_16x16x32_bf16 v[42:45], v[152:155], v[184:187], v[42:45]
	v_mfma_f32_16x16x32_bf16 v[28:31], v[140:143], v[204:207], v[28:31]
	v_mfma_f32_16x16x32_bf16 v[24:27], v[152:155], v[204:207], v[24:27]
	v_mfma_f32_16x16x32_bf16 v[12:15], v[140:143], v[212:215], v[12:15]
	v_mfma_f32_16x16x32_bf16 v[8:11], v[152:155], v[212:215], v[8:11]
	v_mfma_f32_16x16x32_bf16 v[62:65], v[144:147], v[180:183], v[62:65]
	v_mfma_f32_16x16x32_bf16 v[58:61], v[156:159], v[180:183], v[58:61]
	v_mfma_f32_16x16x32_bf16 v[46:49], v[144:147], v[188:191], v[46:49]
	v_mfma_f32_16x16x32_bf16 v[42:45], v[156:159], v[188:191], v[42:45]
	v_mfma_f32_16x16x32_bf16 v[28:31], v[144:147], v[208:211], v[28:31]
	v_mfma_f32_16x16x32_bf16 v[24:27], v[156:159], v[208:211], v[24:27]
	v_mfma_f32_16x16x32_bf16 v[12:15], v[144:147], v[216:219], v[12:15]
	v_mfma_f32_16x16x32_bf16 v[8:11], v[156:159], v[216:219], v[8:11]
	v_mfma_f32_16x16x32_bf16 v[54:57], v[160:163], v[176:179], v[54:57]
	v_mfma_f32_16x16x32_bf16 v[50:53], v[168:171], v[176:179], v[50:53]
	v_mfma_f32_16x16x32_bf16 v[38:41], v[160:163], v[184:187], v[38:41]
	v_mfma_f32_16x16x32_bf16 v[34:37], v[168:171], v[184:187], v[34:37]
	v_mfma_f32_16x16x32_bf16 v[20:23], v[160:163], v[204:207], v[20:23]
	v_mfma_f32_16x16x32_bf16 v[16:19], v[168:171], v[204:207], v[16:19]
	v_mfma_f32_16x16x32_bf16 v[4:7], v[160:163], v[212:215], v[4:7]
	v_mfma_f32_16x16x32_bf16 v[0:3], v[168:171], v[212:215], v[0:3]
	v_mfma_f32_16x16x32_bf16 v[54:57], v[164:167], v[180:183], v[54:57]
	v_mfma_f32_16x16x32_bf16 v[50:53], v[172:175], v[180:183], v[50:53]
	v_mfma_f32_16x16x32_bf16 v[38:41], v[164:167], v[188:191], v[38:41]
	v_mfma_f32_16x16x32_bf16 v[34:37], v[172:175], v[188:191], v[34:37]
	v_mfma_f32_16x16x32_bf16 v[20:23], v[164:167], v[208:211], v[20:23]
	v_mfma_f32_16x16x32_bf16 v[16:19], v[172:175], v[208:211], v[16:19]
	v_mfma_f32_16x16x32_bf16 v[4:7], v[164:167], v[216:219], v[4:7]
	v_mfma_f32_16x16x32_bf16 v[0:3], v[172:175], v[216:219], v[0:3]
	s_setprio 0
	s_barrier
	s_add_i32 s44, s44, 2
	s_add_u32 s6, s6, 0x100
	s_addc_u32 s7, s7, 0
	s_add_u32 s42, s42, 0x100
	s_addc_u32 s43, s43, 0
	s_cmp_gt_u32 s44, 13
	s_cbranch_scc0 .LBB0_388
	s_and_b64 vcc, exec, s[10:11]
	s_cbranch_vccz .LBB0_391
	s_barrier

; #define PG8_STAGE(bufoff, gbase, voff) do { _Pragma("unroll") for (int _i = 0; _i < 2; ++_i) \
;         __builtin_amdgcn_global_load_lds((const unsigned*)((const char*)(gbase) + (voff)[_i]), (PG8_LAS unsigned*)(lds + (bufoff) + ldsw + _i * 8192), 16, 0, 0); } while (0)
; #define PG8_LDA(dst, b, h) do { _Pragma("unroll") for (int m = 0; m < 4; ++m) _Pragma("unroll") for (int k = 0; k < 2; ++k) dst[m][k] = *(const PG8_LAS bf16x8*)(lds + PG8_SA(b, h) + aoff + m * 2048 + k * 1024); } while (0)
; #define PG8_LDB(dst, b, h) do { _Pragma("unroll") for (int n = 0; n < 2; ++n) _Pragma("unroll") for (int k = 0; k < 2; ++k) dst[n][k] = *(const PG8_LAS bf16x8*)(lds + PG8_SB(b, h) + boff + n * 2048 + k * 1024); } while (0)
; #define PG8_MMA(ai, bj, At, Bt) do { __builtin_amdgcn_s_setprio(1); _Pragma("unroll") for (int m = 0; m < 4; ++m) _Pragma("unroll") for (int n = 0; n < 2; ++n) _Pragma("unroll") for (int k = 0; k < 2; ++k) \
;         acc[ai][bj][m][n] = __builtin_amdgcn_mfma_f32_16x16x32_bf16(Bt[n][k], At[m][k], acc[ai][bj][m][n], 0, 0, 0); __builtin_amdgcn_s_setprio(0); } while (0)
; #define PG8_WAIT_V(n) asm volatile("s_waitcnt vmcnt(" #n ")" ::: "memory")
; #define PG8_WAIT_L(n) asm volatile("s_waitcnt lgkmcnt(" #n ")" ::: "memory")
; #define PG8_BAR __builtin_amdgcn_s_barrier()
; #define PG8_SCHED __builtin_amdgcn_sched_barrier(0)
; template <class Epi, class Sched, bool ALIGN_EPI = false, bool SP2 = false>
; __device__ __forceinline__ void gemm_phase(PG8_LAS unsigned char* lds, const Gemm g, const Sched& S, const Epi& E, int tid_in) {
;     ...
;             const bool last = (t == nt - 2);
;             const char* a1 = cA + (size_t)(t + 1) * kstep;
;             const char* a2 = last ? nA : cA + (size_t)(t + 2) * kstep; const char* b2 = last ? nB : cB + (size_t)(t + 2) * kstep;
;             const char* a3 = a2 + kstep; const char* b3 = b2 + kstep;
;             if (last && has_next) S.a_ready(nxt);
;             if constexpr (SP2) {
;             PG8_LDB(B0, 0, 0); PG8_LDB(B1, 0, 1); PG8_SCHED; PG8_LDA(At, 0, 0); PG8_STAGE(PG8_SA(1, 1), a1 + hstep, voffA);
;             PG8_WAIT_V(8); PG8_WAIT_L(0); PG8_BAR; PG8_MMA(0, 0, At, B0); PG8_MMA(0, 1, At, B1); PG8_BAR; PG8_SCHED;
;             PG8_LDA(At, 0, 1); PG8_STAGE(PG8_SB(0, 0), b2, voffB); PG8_STAGE(PG8_SB(0, 1), b2 + hstep, voffB); PG8_STAGE(PG8_SA(0, 0), a2, voffA);
.LBB0_920:
	s_add_u32 s26, s2, 0xfffc0080
	s_addc_u32 s27, s3, -1
	s_add_i32 s51, 0, 0x10000
	s_cmp_eq_u32 s50, 12
	s_cselect_b32 s29, s21, s27
	s_cselect_b32 s28, s46, s26
	s_cselect_b32 s27, s19, s49
	s_cselect_b32 s26, s47, s48
	s_add_i32 s54, 0, 0x14000
	v_add_u32_e32 v142, s51, v217
	v_add_u32_e32 v158, s54, v217
	ds_read_b128 v[130:133], v142
	ds_read_b128 v[134:137], v142 offset:1024
	ds_read_b128 v[138:141], v142 offset:2048
	ds_read_b128 v[142:145], v142 offset:3072
	ds_read_b128 v[146:149], v158
	ds_read_b128 v[150:153], v158 offset:1024
	ds_read_b128 v[154:157], v158 offset:2048
	ds_read_b128 v[158:161], v158 offset:3072
	v_lshl_add_u64 v[192:193], s[2:3], 0, v[184:185]
	s_add_i32 m0, s37, 0xc000
	ds_read_b128 v[162:165], v219
	ds_read_b128 v[166:169], v219 offset:1024
	ds_read_b128 v[170:173], v219 offset:2048
	ds_read_b128 v[174:177], v219 offset:3072
	ds_read_b128 v[188:191], v219 offset:4096
	ds_read_b128 v[204:207], v219 offset:5120
	ds_read_b128 v[208:211], v219 offset:6144
	ds_read_b128 v[212:215], v219 offset:7168
	global_load_lds_dwordx4 v[192:193], off
	v_lshl_add_u64 v[192:193], s[2:3], 0, v[186:187]
	s_add_i32 m0, s37, 0xe000
	s_nop 0
	global_load_lds_dwordx4 v[192:193], off
	s_waitcnt vmcnt(8)
	s_waitcnt lgkmcnt(0)
	s_barrier
	s_setprio 1
	s_waitcnt lgkmcnt(0)
	v_mfma_f32_16x16x32_bf16 v[126:129], v[130:133], v[162:165], v[126:129]
	v_mfma_f32_16x16x32_bf16 v[122:125], v[138:141], v[162:165], v[122:125]
	v_mfma_f32_16x16x32_bf16 v[110:113], v[130:133], v[170:173], v[110:113]
	v_mfma_f32_16x16x32_bf16 v[106:109], v[138:141], v[170:173], v[106:109]
	v_mfma_f32_16x16x32_bf16 v[94:97], v[130:133], v[188:191], v[94:97]
	v_mfma_f32_16x16x32_bf16 v[90:93], v[138:141], v[188:191], v[90:93]
	v_mfma_f32_16x16x32_bf16 v[78:81], v[130:133], v[208:211], v[78:81]
	v_mfma_f32_16x16x32_bf16 v[74:77], v[138:141], v[208:211], v[74:77]
	v_mfma_f32_16x16x32_bf16 v[126:129], v[134:137], v[166:169], v[126:129]
	v_mfma_f32_16x16x32_bf16 v[122:125], v[142:145], v[166:169], v[122:125]
	v_mfma_f32_16x16x32_bf16 v[110:113], v[134:137], v[174:177], v[110:113]
	v_mfma_f32_16x16x32_bf16 v[106:109], v[142:145], v[174:177], v[106:109]
	v_mfma_f32_16x16x32_bf16 v[94:97], v[134:137], v[204:207], v[94:97]
	v_mfma_f32_16x16x32_bf16 v[90:93], v[142:145], v[204:207], v[90:93]
	v_mfma_f32_16x16x32_bf16 v[78:81], v[134:137], v[212:215], v[78:81]
	v_mfma_f32_16x16x32_bf16 v[74:77], v[142:145], v[212:215], v[74:77]
	v_mfma_f32_16x16x32_bf16 v[118:121], v[146:149], v[162:165], v[118:121]
	v_mfma_f32_16x16x32_bf16 v[114:117], v[154:157], v[162:165], v[114:117]
	v_mfma_f32_16x16x32_bf16 v[102:105], v[146:149], v[170:173], v[102:105]
	v_mfma_f32_16x16x32_bf16 v[98:101], v[154:157], v[170:173], v[98:101]
	v_mfma_f32_16x16x32_bf16 v[86:89], v[146:149], v[188:191], v[86:89]
	v_mfma_f32_16x16x32_bf16 v[82:85], v[154:157], v[188:191], v[82:85]
	v_mfma_f32_16x16x32_bf16 v[70:73], v[146:149], v[208:211], v[70:73]
	v_mfma_f32_16x16x32_bf16 v[66:69], v[154:157], v[208:211], v[66:69]
	v_mfma_f32_16x16x32_bf16 v[118:121], v[150:153], v[166:169], v[118:121]
	v_mfma_f32_16x16x32_bf16 v[114:117], v[158:161], v[166:169], v[114:117]
	v_mfma_f32_16x16x32_bf16 v[102:105], v[150:153], v[174:177], v[102:105]
	v_mfma_f32_16x16x32_bf16 v[98:101], v[158:161], v[174:177], v[98:101]
	v_mfma_f32_16x16x32_bf16 v[86:89], v[150:153], v[204:207], v[86:89]
	v_mfma_f32_16x16x32_bf16 v[82:85], v[158:161], v[204:207], v[82:85]
	v_mfma_f32_16x16x32_bf16 v[70:73], v[150:153], v[212:215], v[70:73]
	v_mfma_f32_16x16x32_bf16 v[66:69], v[158:161], v[212:215], v[66:69]
	s_setprio 0
	s_barrier
	s_add_i32 s51, s51, s36
	v_lshl_add_u64 v[192:193], s[26:27], 0, v[32:33]
	s_mov_b32 m0, s51
	ds_read_b128 v[162:165], v219 offset:16384
	ds_read_b128 v[166:169], v219 offset:17408
	ds_read_b128 v[170:173], v219 offset:18432
	ds_read_b128 v[174:177], v219 offset:19456
	ds_read_b128 v[188:191], v219 offset:20480
	ds_read_b128 v[204:207], v219 offset:21504
	ds_read_b128 v[208:211], v219 offset:22528
	ds_read_b128 v[212:215], v219 offset:23552
	global_load_lds_dwordx4 v[192:193], off
	s_add_i32 m0, s51, 0x2000
	s_add_u32 s52, s26, 0x40000
	v_lshl_add_u64 v[220:221], s[26:27], 0, v[178:179]
	s_addc_u32 s53, s27, 0
	s_add_i32 s51, s54, s36
	global_load_lds_dwordx4 v[220:221], off
	v_lshl_add_u64 v[222:223], s[52:53], 0, v[32:33]
	s_mov_b32 m0, s51
	v_lshl_add_u64 v[224:225], s[28:29], 0, v[180:181]
	global_load_lds_dwordx4 v[222:223], off
	v_lshl_add_u64 v[222:223], s[52:53], 0, v[178:179]
	s_add_i32 m0, s51, 0x2000
	s_nop 0
	global_load_lds_dwordx4 v[222:223], off
	v_lshl_add_u64 v[222:223], s[28:29], 0, v[182:183]
	s_mov_b32 m0, s37
	s_nop 0
	global_load_lds_dwordx4 v[222:223], off
	s_mov_b32 m0, s38
	s_nop 0
	global_load_lds_dwordx4 v[224:225], off
	s_waitcnt vmcnt(8)
	s_waitcnt lgkmcnt(0)
	s_barrier
; #define PG8_STAGE(bufoff, gbase, voff) do { _Pragma("unroll") for (int _i = 0; _i < 2; ++_i) \
;         __builtin_amdgcn_global_load_lds((const unsigned*)((const char*)(gbase) + (voff)[_i]), (PG8_LAS unsigned*)(lds + (bufoff) + ldsw + _i * 8192), 16, 0, 0); } while (0)
; #define PG8_LDA(dst, b, h) do { _Pragma("unroll") for (int m = 0; m < 4; ++m) _Pragma("unroll") for (int k = 0; k < 2; ++k) dst[m][k] = *(const PG8_LAS bf16x8*)(lds + PG8_SA(b, h) + aoff + m * 2048 + k * 1024); } while (0)
; #define PG8_LDB(dst, b, h) do { _Pragma("unroll") for (int n = 0; n < 2; ++n) _Pragma("unroll") for (int k = 0; k < 2; ++k) dst[n][k] = *(const PG8_LAS bf16x8*)(lds + PG8_SB(b, h) + boff + n * 2048 + k * 1024); } while (0)
; #define PG8_MMA(ai, bj, At, Bt) do { __builtin_amdgcn_s_setprio(1); _Pragma("unroll") for (int m = 0; m < 4; ++m) _Pragma("unroll") for (int n = 0; n < 2; ++n) _Pragma("unroll") for (int k = 0; k < 2; ++k) \
;         acc[ai][bj][m][n] = __builtin_amdgcn_mfma_f32_16x16x32_bf16(Bt[n][k], At[m][k], acc[ai][bj][m][n], 0, 0, 0); __builtin_amdgcn_s_setprio(0); } while (0)
; #define PG8_WAIT_V(n) asm volatile("s_waitcnt vmcnt(" #n ")" ::: "memory")
; #define PG8_WAIT_L(n) asm volatile("s_waitcnt lgkmcnt(" #n ")" ::: "memory")
; #define PG8_BAR __builtin_amdgcn_s_barrier()
; #define PG8_SCHED __builtin_amdgcn_sched_barrier(0)
; template <class Epi, class Sched, bool ALIGN_EPI = false, bool SP2 = false>
; __device__ __forceinline__ void gemm_phase(PG8_LAS unsigned char* lds, const Gemm g, const Sched& S, const Epi& E, int tid_in) {
;     ...
;             PG8_WAIT_V(8); PG8_WAIT_L(0); PG8_BAR; PG8_MMA(1, 0, At, B0); PG8_MMA(1, 1, At, B1); PG8_BAR; PG8_SCHED;
;             PG8_LDB(B0, 1, 0); PG8_LDB(B1, 1, 1); PG8_SCHED; PG8_LDA(At, 1, 0); PG8_STAGE(PG8_SA(0, 1), a2 + hstep, voffA);
;             PG8_WAIT_V(8); PG8_WAIT_L(0); PG8_BAR; PG8_MMA(0, 0, At, B0); PG8_MMA(0, 1, At, B1); PG8_BAR; PG8_SCHED;
	s_setprio 1
	s_waitcnt lgkmcnt(0)
	v_mfma_f32_16x16x32_bf16 v[62:65], v[130:133], v[162:165], v[62:65]
	v_mfma_f32_16x16x32_bf16 v[58:61], v[138:141], v[162:165], v[58:61]
	v_mfma_f32_16x16x32_bf16 v[46:49], v[130:133], v[170:173], v[46:49]
	v_mfma_f32_16x16x32_bf16 v[42:45], v[138:141], v[170:173], v[42:45]
	v_mfma_f32_16x16x32_bf16 v[28:31], v[130:133], v[188:191], v[28:31]
	v_mfma_f32_16x16x32_bf16 v[24:27], v[138:141], v[188:191], v[24:27]
	v_mfma_f32_16x16x32_bf16 v[12:15], v[130:133], v[208:211], v[12:15]
	v_mfma_f32_16x16x32_bf16 v[8:11], v[138:141], v[208:211], v[8:11]
	v_mfma_f32_16x16x32_bf16 v[62:65], v[134:137], v[166:169], v[62:65]
	v_mfma_f32_16x16x32_bf16 v[58:61], v[142:145], v[166:169], v[58:61]
	v_mfma_f32_16x16x32_bf16 v[46:49], v[134:137], v[174:177], v[46:49]
	v_mfma_f32_16x16x32_bf16 v[42:45], v[142:145], v[174:177], v[42:45]
	v_mfma_f32_16x16x32_bf16 v[28:31], v[134:137], v[204:207], v[28:31]
	v_mfma_f32_16x16x32_bf16 v[24:27], v[142:145], v[204:207], v[24:27]
	v_mfma_f32_16x16x32_bf16 v[12:15], v[134:137], v[212:215], v[12:15]
	v_mfma_f32_16x16x32_bf16 v[8:11], v[142:145], v[212:215], v[8:11]
	v_mfma_f32_16x16x32_bf16 v[54:57], v[146:149], v[162:165], v[54:57]
	v_mfma_f32_16x16x32_bf16 v[50:53], v[154:157], v[162:165], v[50:53]
	v_mfma_f32_16x16x32_bf16 v[38:41], v[146:149], v[170:173], v[38:41]
	v_mfma_f32_16x16x32_bf16 v[34:37], v[154:157], v[170:173], v[34:37]
	v_mfma_f32_16x16x32_bf16 v[20:23], v[146:149], v[188:191], v[20:23]
	v_mfma_f32_16x16x32_bf16 v[16:19], v[154:157], v[188:191], v[16:19]
	v_mfma_f32_16x16x32_bf16 v[4:7], v[146:149], v[208:211], v[4:7]
	v_mfma_f32_16x16x32_bf16 v[0:3], v[154:157], v[208:211], v[0:3]
	v_mfma_f32_16x16x32_bf16 v[54:57], v[150:153], v[166:169], v[54:57]
	v_mfma_f32_16x16x32_bf16 v[50:53], v[158:161], v[166:169], v[50:53]
	v_mfma_f32_16x16x32_bf16 v[38:41], v[150:153], v[174:177], v[38:41]
	v_mfma_f32_16x16x32_bf16 v[34:37], v[158:161], v[174:177], v[34:37]
	v_mfma_f32_16x16x32_bf16 v[20:23], v[150:153], v[204:207], v[20:23]
	v_mfma_f32_16x16x32_bf16 v[16:19], v[158:161], v[204:207], v[16:19]
	v_mfma_f32_16x16x32_bf16 v[4:7], v[150:153], v[212:215], v[4:7]
	v_mfma_f32_16x16x32_bf16 v[0:3], v[158:161], v[212:215], v[0:3]
	s_setprio 0
	s_barrier
	s_add_i32 s51, 0, 0x18000
	s_add_i32 s52, 0, 0x1c000
	v_add_u32_e32 v142, s51, v217
	v_add_u32_e32 v158, s52, v217
	ds_read_b128 v[130:133], v142
	ds_read_b128 v[134:137], v142 offset:1024
	ds_read_b128 v[138:141], v142 offset:2048
	ds_read_b128 v[142:145], v142 offset:3072
	ds_read_b128 v[146:149], v158
	ds_read_b128 v[150:153], v158 offset:1024
	ds_read_b128 v[154:157], v158 offset:2048
	ds_read_b128 v[158:161], v158 offset:3072
	s_add_u32 s28, s28, 0x40000
	s_addc_u32 s29, s29, 0
	s_mov_b32 m0, s39
	v_lshl_add_u64 v[226:227], s[28:29], 0, v[182:183]
	ds_read_b128 v[162:165], v219 offset:32768
	ds_read_b128 v[166:169], v219 offset:33792
	ds_read_b128 v[170:173], v219 offset:34816
	ds_read_b128 v[174:177], v219 offset:35840
	ds_read_b128 v[188:191], v219 offset:36864
	ds_read_b128 v[204:207], v219 offset:37888
	ds_read_b128 v[208:211], v219 offset:38912
	ds_read_b128 v[212:215], v219 offset:39936
	global_load_lds_dwordx4 v[226:227], off
	v_lshl_add_u64 v[226:227], s[28:29], 0, v[180:181]
	s_mov_b32 m0, s40
	s_nop 0
	global_load_lds_dwordx4 v[226:227], off
	s_waitcnt vmcnt(8)
	s_waitcnt lgkmcnt(0)
	s_barrier
	s_setprio 1
	s_waitcnt lgkmcnt(0)
	v_mfma_f32_16x16x32_bf16 v[126:129], v[130:133], v[162:165], v[126:129]
	v_mfma_f32_16x16x32_bf16 v[122:125], v[138:141], v[162:165], v[122:125]
	v_mfma_f32_16x16x32_bf16 v[110:113], v[130:133], v[170:173], v[110:113]
	v_mfma_f32_16x16x32_bf16 v[106:109], v[138:141], v[170:173], v[106:109]
	v_mfma_f32_16x16x32_bf16 v[94:97], v[130:133], v[188:191], v[94:97]
	v_mfma_f32_16x16x32_bf16 v[90:93], v[138:141], v[188:191], v[90:93]
	v_mfma_f32_16x16x32_bf16 v[78:81], v[130:133], v[208:211], v[78:81]
	v_mfma_f32_16x16x32_bf16 v[74:77], v[138:141], v[208:211], v[74:77]
	v_mfma_f32_16x16x32_bf16 v[126:129], v[134:137], v[166:169], v[126:129]
	v_mfma_f32_16x16x32_bf16 v[122:125], v[142:145], v[166:169], v[122:125]
	v_mfma_f32_16x16x32_bf16 v[110:113], v[134:137], v[174:177], v[110:113]
	v_mfma_f32_16x16x32_bf16 v[106:109], v[142:145], v[174:177], v[106:109]
	v_mfma_f32_16x16x32_bf16 v[94:97], v[134:137], v[204:207], v[94:97]
	v_mfma_f32_16x16x32_bf16 v[90:93], v[142:145], v[204:207], v[90:93]
	v_mfma_f32_16x16x32_bf16 v[78:81], v[134:137], v[212:215], v[78:81]
	v_mfma_f32_16x16x32_bf16 v[74:77], v[142:145], v[212:215], v[74:77]
	v_mfma_f32_16x16x32_bf16 v[118:121], v[146:149], v[162:165], v[118:121]
	v_mfma_f32_16x16x32_bf16 v[114:117], v[154:157], v[162:165], v[114:117]
	v_mfma_f32_16x16x32_bf16 v[102:105], v[146:149], v[170:173], v[102:105]
	v_mfma_f32_16x16x32_bf16 v[98:101], v[154:157], v[170:173], v[98:101]
	v_mfma_f32_16x16x32_bf16 v[86:89], v[146:149], v[188:191], v[86:89]
	v_mfma_f32_16x16x32_bf16 v[82:85], v[154:157], v[188:191], v[82:85]
	v_mfma_f32_16x16x32_bf16 v[70:73], v[146:149], v[208:211], v[70:73]
	v_mfma_f32_16x16x32_bf16 v[66:69], v[154:157], v[208:211], v[66:69]
	v_mfma_f32_16x16x32_bf16 v[118:121], v[150:153], v[166:169], v[118:121]
	v_mfma_f32_16x16x32_bf16 v[114:117], v[158:161], v[166:169], v[114:117]
	v_mfma_f32_16x16x32_bf16 v[102:105], v[150:153], v[174:177], v[102:105]
	v_mfma_f32_16x16x32_bf16 v[98:101], v[158:161], v[174:177], v[98:101]
	v_mfma_f32_16x16x32_bf16 v[86:89], v[150:153], v[204:207], v[86:89]
	v_mfma_f32_16x16x32_bf16 v[82:85], v[158:161], v[204:207], v[82:85]
	v_mfma_f32_16x16x32_bf16 v[70:73], v[150:153], v[212:215], v[70:73]
	v_mfma_f32_16x16x32_bf16 v[66:69], v[158:161], v[212:215], v[66:69]
	s_setprio 0
	s_barrier
; #define PG8_STAGE(bufoff, gbase, voff) do { _Pragma("unroll") for (int _i = 0; _i < 2; ++_i) \
;         __builtin_amdgcn_global_load_lds((const unsigned*)((const char*)(gbase) + (voff)[_i]), (PG8_LAS unsigned*)(lds + (bufoff) + ldsw + _i * 8192), 16, 0, 0); } while (0)
; #define PG8_LDA(dst, b, h) do { _Pragma("unroll") for (int m = 0; m < 4; ++m) _Pragma("unroll") for (int k = 0; k < 2; ++k) dst[m][k] = *(const PG8_LAS bf16x8*)(lds + PG8_SA(b, h) + aoff + m * 2048 + k * 1024); } while (0)
; #define PG8_MMA(ai, bj, At, Bt) do { __builtin_amdgcn_s_setprio(1); _Pragma("unroll") for (int m = 0; m < 4; ++m) _Pragma("unroll") for (int n = 0; n < 2; ++n) _Pragma("unroll") for (int k = 0; k < 2; ++k) \
;         acc[ai][bj][m][n] = __builtin_amdgcn_mfma_f32_16x16x32_bf16(Bt[n][k], At[m][k], acc[ai][bj][m][n], 0, 0, 0); __builtin_amdgcn_s_setprio(0); } while (0)
; #define PG8_WAIT_V(n) asm volatile("s_waitcnt vmcnt(" #n ")" ::: "memory")
; #define PG8_WAIT_L(n) asm volatile("s_waitcnt lgkmcnt(" #n ")" ::: "memory")
; #define PG8_BAR __builtin_amdgcn_s_barrier()
; #define PG8_SCHED __builtin_amdgcn_sched_barrier(0)
; template <class Epi, class Sched, bool ALIGN_EPI = false, bool SP2 = false>
; __device__ __forceinline__ void gemm_phase(PG8_LAS unsigned char* lds, const Gemm g, const Sched& S, const Epi& E, int tid_in) {
;     ...
;             PG8_LDA(At, 1, 1); PG8_STAGE(PG8_SB(1, 0), b3, voffB); PG8_STAGE(PG8_SB(1, 1), b3 + hstep, voffB); PG8_STAGE(PG8_SA(1, 0), a3, voffA);
;             PG8_WAIT_V(8); PG8_WAIT_L(0); PG8_BAR; PG8_MMA(1, 0, At, B0); PG8_MMA(1, 1, At, B1); PG8_BAR; PG8_SCHED;
;     ...
;         if constexpr (ALIGN_EPI) { if (wr == 0) PG8_BAR; }
	s_add_i32 s28, s51, s36
	v_lshl_add_u64 v[192:193], v[192:193], 0, s[84:85]
	s_mov_b32 m0, s28
	ds_read_b128 v[162:165], v219 offset:49152
	ds_read_b128 v[166:169], v219 offset:50176
	ds_read_b128 v[170:173], v219 offset:51200
	ds_read_b128 v[174:177], v219 offset:52224
	ds_read_b128 v[188:191], v219 offset:53248
	ds_read_b128 v[204:207], v219 offset:54272
	ds_read_b128 v[208:211], v219 offset:55296
	ds_read_b128 v[212:215], v219 offset:56320
	global_load_lds_dwordx4 v[192:193], off
	s_add_i32 m0, s28, 0x2000
	s_add_u32 s26, s26, 0x40080
	v_lshl_add_u64 v[192:193], v[220:221], 0, s[84:85]
	s_addc_u32 s27, s27, 0
	s_add_i32 s28, s52, s36
	global_load_lds_dwordx4 v[192:193], off
	v_lshl_add_u64 v[192:193], s[26:27], 0, v[32:33]
	s_mov_b32 m0, s28
	s_nop 0
	global_load_lds_dwordx4 v[192:193], off
	v_lshl_add_u64 v[192:193], s[26:27], 0, v[178:179]
	s_add_i32 m0, s28, 0x2000
	s_nop 0
	global_load_lds_dwordx4 v[192:193], off
	v_lshl_add_u64 v[192:193], v[222:223], 0, s[84:85]
	s_mov_b32 m0, s41
	s_nop 0
	global_load_lds_dwordx4 v[192:193], off
	v_lshl_add_u64 v[192:193], v[224:225], 0, s[84:85]
	s_mov_b32 m0, s42
	s_nop 0
	global_load_lds_dwordx4 v[192:193], off
	s_waitcnt vmcnt(8)
	s_waitcnt lgkmcnt(0)
	s_barrier
	s_setprio 1
	s_waitcnt lgkmcnt(0)
	v_mfma_f32_16x16x32_bf16 v[62:65], v[130:133], v[162:165], v[62:65]
	v_mfma_f32_16x16x32_bf16 v[58:61], v[138:141], v[162:165], v[58:61]
	v_mfma_f32_16x16x32_bf16 v[46:49], v[130:133], v[170:173], v[46:49]
	v_mfma_f32_16x16x32_bf16 v[42:45], v[138:141], v[170:173], v[42:45]
	v_mfma_f32_16x16x32_bf16 v[28:31], v[130:133], v[188:191], v[28:31]
	v_mfma_f32_16x16x32_bf16 v[24:27], v[138:141], v[188:191], v[24:27]
	v_mfma_f32_16x16x32_bf16 v[12:15], v[130:133], v[208:211], v[12:15]
	v_mfma_f32_16x16x32_bf16 v[8:11], v[138:141], v[208:211], v[8:11]
	v_mfma_f32_16x16x32_bf16 v[62:65], v[134:137], v[166:169], v[62:65]
	v_mfma_f32_16x16x32_bf16 v[58:61], v[142:145], v[166:169], v[58:61]
	v_mfma_f32_16x16x32_bf16 v[46:49], v[134:137], v[174:177], v[46:49]
	v_mfma_f32_16x16x32_bf16 v[42:45], v[142:145], v[174:177], v[42:45]
	v_mfma_f32_16x16x32_bf16 v[28:31], v[134:137], v[204:207], v[28:31]
	v_mfma_f32_16x16x32_bf16 v[24:27], v[142:145], v[204:207], v[24:27]
	v_mfma_f32_16x16x32_bf16 v[12:15], v[134:137], v[212:215], v[12:15]
	v_mfma_f32_16x16x32_bf16 v[8:11], v[142:145], v[212:215], v[8:11]
	v_mfma_f32_16x16x32_bf16 v[54:57], v[146:149], v[162:165], v[54:57]
	v_mfma_f32_16x16x32_bf16 v[50:53], v[154:157], v[162:165], v[50:53]
	v_mfma_f32_16x16x32_bf16 v[38:41], v[146:149], v[170:173], v[38:41]
	v_mfma_f32_16x16x32_bf16 v[34:37], v[154:157], v[170:173], v[34:37]
	v_mfma_f32_16x16x32_bf16 v[20:23], v[146:149], v[188:191], v[20:23]
	v_mfma_f32_16x16x32_bf16 v[16:19], v[154:157], v[188:191], v[16:19]
	v_mfma_f32_16x16x32_bf16 v[4:7], v[146:149], v[208:211], v[4:7]
	v_mfma_f32_16x16x32_bf16 v[0:3], v[154:157], v[208:211], v[0:3]
	v_mfma_f32_16x16x32_bf16 v[54:57], v[150:153], v[166:169], v[54:57]
	v_mfma_f32_16x16x32_bf16 v[50:53], v[158:161], v[166:169], v[50:53]
	v_mfma_f32_16x16x32_bf16 v[38:41], v[150:153], v[174:177], v[38:41]
	v_mfma_f32_16x16x32_bf16 v[34:37], v[158:161], v[174:177], v[34:37]
	v_mfma_f32_16x16x32_bf16 v[20:23], v[150:153], v[204:207], v[20:23]
	v_mfma_f32_16x16x32_bf16 v[16:19], v[158:161], v[204:207], v[16:19]
	v_mfma_f32_16x16x32_bf16 v[4:7], v[150:153], v[212:215], v[4:7]
	v_mfma_f32_16x16x32_bf16 v[0:3], v[158:161], v[212:215], v[0:3]
	s_setprio 0
	s_barrier
	s_add_i32 s50, s50, 2
	s_add_u32 s2, s2, 0x100
	s_addc_u32 s3, s3, 0
	s_add_u32 s48, s48, 0x100
	s_addc_u32 s49, s49, 0
	s_cmp_gt_u32 s50, 13
	s_cbranch_scc0 .LBB0_920
	s_and_b64 vcc, exec, s[16:17]
	s_cbranch_vccz .LBB0_923
	s_barrier

; #define PG8_STAGE(bufoff, gbase, voff) do { _Pragma("unroll") for (int _i = 0; _i < 2; ++_i) \
;         __builtin_amdgcn_global_load_lds((const unsigned*)((const char*)(gbase) + (voff)[_i]), (PG8_LAS unsigned*)(lds + (bufoff) + ldsw + _i * 8192), 16, 0, 0); } while (0)
; #define PG8_LDA(dst, b, h) do { _Pragma("unroll") for (int m = 0; m < 4; ++m) _Pragma("unroll") for (int k = 0; k < 2; ++k) dst[m][k] = *(const PG8_LAS bf16x8*)(lds + PG8_SA(b, h) + aoff + m * 2048 + k * 1024); } while (0)
; #define PG8_LDB(dst, b, h) do { _Pragma("unroll") for (int n = 0; n < 2; ++n) _Pragma("unroll") for (int k = 0; k < 2; ++k) dst[n][k] = *(const PG8_LAS bf16x8*)(lds + PG8_SB(b, h) + boff + n * 2048 + k * 1024); } while (0)
; #define PG8_MMA(ai, bj, At, Bt) do { __builtin_amdgcn_s_setprio(1); _Pragma("unroll") for (int m = 0; m < 4; ++m) _Pragma("unroll") for (int n = 0; n < 2; ++n) _Pragma("unroll") for (int k = 0; k < 2; ++k) \
;         acc[ai][bj][m][n] = __builtin_amdgcn_mfma_f32_16x16x32_bf16(Bt[n][k], At[m][k], acc[ai][bj][m][n], 0, 0, 0); __builtin_amdgcn_s_setprio(0); } while (0)
; #define PG8_WAIT_V(n) asm volatile("s_waitcnt vmcnt(" #n ")" ::: "memory")
; #define PG8_WAIT_L(n) asm volatile("s_waitcnt lgkmcnt(" #n ")" ::: "memory")
; #define PG8_BAR __builtin_amdgcn_s_barrier()
; #define PG8_SCHED __builtin_amdgcn_sched_barrier(0)
; template <class Epi, class Sched, bool ALIGN_EPI = false, bool SP2 = false>
; __device__ __forceinline__ void gemm_phase(PG8_LAS unsigned char* lds, const Gemm g, const Sched& S, const Epi& E, int tid_in) {
;     ...
;             const bool last = (t == nt - 2);
;             const char* a1 = cA + (size_t)(t + 1) * kstep;
;             const char* a2 = last ? nA : cA + (size_t)(t + 2) * kstep; const char* b2 = last ? nB : cB + (size_t)(t + 2) * kstep;
;             const char* a3 = a2 + kstep; const char* b3 = b2 + kstep;
;             if (last && has_next) S.a_ready(nxt);
;             if constexpr (SP2) {
;             PG8_LDB(B0, 0, 0); PG8_LDB(B1, 0, 1); PG8_SCHED; PG8_LDA(At, 0, 0); PG8_STAGE(PG8_SA(1, 1), a1 + hstep, voffA);
;             PG8_WAIT_V(8); PG8_WAIT_L(0); PG8_BAR; PG8_MMA(0, 0, At, B0); PG8_MMA(0, 1, At, B1); PG8_BAR; PG8_SCHED;
;             PG8_LDA(At, 0, 1); PG8_STAGE(PG8_SB(0, 0), b2, voffB); PG8_STAGE(PG8_SB(0, 1), b2 + hstep, voffB); PG8_STAGE(PG8_SA(0, 0), a2, voffA);
.LBB0_1010:
	s_add_u32 s6, s2, 0x100
	s_addc_u32 s7, s3, 0
	s_add_i32 s52, 0, 0x10000
	s_cmp_eq_u32 s51, 40
	s_cselect_b32 s29, s23, s7
	s_cselect_b32 s28, s22, s6
	s_cselect_b32 s27, s25, s50
	s_cselect_b32 s26, s24, s49
	s_add_i32 s53, 0, 0x14000
	v_add_u32_e32 v142, s52, v248
	v_add_u32_e32 v158, s53, v248
	ds_read_b128 v[130:133], v142
	ds_read_b128 v[134:137], v142 offset:1024
	ds_read_b128 v[138:141], v142 offset:2048
	ds_read_b128 v[142:145], v142 offset:3072
	ds_read_b128 v[146:149], v158
	ds_read_b128 v[150:153], v158 offset:1024
	ds_read_b128 v[154:157], v158 offset:2048
	ds_read_b128 v[158:161], v158 offset:3072
	v_lshl_add_u64 v[214:215], s[2:3], 0, v[210:211]
	s_add_i32 m0, s38, 0xc000
	ds_read_b128 v[162:165], v250
	ds_read_b128 v[166:169], v250 offset:1024
	ds_read_b128 v[170:173], v250 offset:2048
	ds_read_b128 v[174:177], v250 offset:3072
	ds_read_b128 v[178:181], v250 offset:4096
	ds_read_b128 v[182:185], v250 offset:5120
	ds_read_b128 v[186:189], v250 offset:6144
	ds_read_b128 v[190:193], v250 offset:7168
	global_load_lds_dwordx4 v[214:215], off
	v_lshl_add_u64 v[214:215], s[2:3], 0, v[212:213]
	s_add_i32 m0, s38, 0xe000
	s_nop 0
	global_load_lds_dwordx4 v[214:215], off
	s_waitcnt vmcnt(8)
	s_waitcnt lgkmcnt(0)
	s_barrier
	s_setprio 1
	s_waitcnt lgkmcnt(0)
	v_mfma_f32_16x16x32_bf16 v[126:129], v[130:133], v[162:165], v[126:129]
	v_mfma_f32_16x16x32_bf16 v[122:125], v[138:141], v[162:165], v[122:125]
	v_mfma_f32_16x16x32_bf16 v[114:117], v[130:133], v[170:173], v[114:117]
	v_mfma_f32_16x16x32_bf16 v[106:109], v[138:141], v[170:173], v[106:109]
	v_mfma_f32_16x16x32_bf16 v[98:101], v[130:133], v[178:181], v[98:101]
	v_mfma_f32_16x16x32_bf16 v[90:93], v[138:141], v[178:181], v[90:93]
	v_mfma_f32_16x16x32_bf16 v[82:85], v[130:133], v[186:189], v[82:85]
	v_mfma_f32_16x16x32_bf16 v[74:77], v[138:141], v[186:189], v[74:77]
	v_mfma_f32_16x16x32_bf16 v[126:129], v[134:137], v[166:169], v[126:129]
	v_mfma_f32_16x16x32_bf16 v[122:125], v[142:145], v[166:169], v[122:125]
	v_mfma_f32_16x16x32_bf16 v[114:117], v[134:137], v[174:177], v[114:117]
	v_mfma_f32_16x16x32_bf16 v[106:109], v[142:145], v[174:177], v[106:109]
	v_mfma_f32_16x16x32_bf16 v[98:101], v[134:137], v[182:185], v[98:101]
	v_mfma_f32_16x16x32_bf16 v[90:93], v[142:145], v[182:185], v[90:93]
	v_mfma_f32_16x16x32_bf16 v[82:85], v[134:137], v[190:193], v[82:85]
	v_mfma_f32_16x16x32_bf16 v[74:77], v[142:145], v[190:193], v[74:77]
	v_mfma_f32_16x16x32_bf16 v[118:121], v[146:149], v[162:165], v[118:121]
	v_mfma_f32_16x16x32_bf16 v[110:113], v[154:157], v[162:165], v[110:113]
	v_mfma_f32_16x16x32_bf16 v[102:105], v[146:149], v[170:173], v[102:105]
	v_mfma_f32_16x16x32_bf16 v[94:97], v[154:157], v[170:173], v[94:97]
	v_mfma_f32_16x16x32_bf16 v[86:89], v[146:149], v[178:181], v[86:89]
	v_mfma_f32_16x16x32_bf16 v[78:81], v[154:157], v[178:181], v[78:81]
	v_mfma_f32_16x16x32_bf16 v[70:73], v[146:149], v[186:189], v[70:73]
	v_mfma_f32_16x16x32_bf16 v[66:69], v[154:157], v[186:189], v[66:69]
	v_mfma_f32_16x16x32_bf16 v[118:121], v[150:153], v[166:169], v[118:121]
	v_mfma_f32_16x16x32_bf16 v[110:113], v[158:161], v[166:169], v[110:113]
	v_mfma_f32_16x16x32_bf16 v[102:105], v[150:153], v[174:177], v[102:105]
	v_mfma_f32_16x16x32_bf16 v[94:97], v[158:161], v[174:177], v[94:97]
	v_mfma_f32_16x16x32_bf16 v[86:89], v[150:153], v[182:185], v[86:89]
	v_mfma_f32_16x16x32_bf16 v[78:81], v[158:161], v[182:185], v[78:81]
	v_mfma_f32_16x16x32_bf16 v[70:73], v[150:153], v[190:193], v[70:73]
	v_mfma_f32_16x16x32_bf16 v[66:69], v[158:161], v[190:193], v[66:69]
	s_setprio 0
	s_barrier
	s_add_i32 s2, s52, s31
	v_lshl_add_u64 v[214:215], s[26:27], 0, v[32:33]
	s_mov_b32 m0, s2
	ds_read_b128 v[162:165], v250 offset:16384
	ds_read_b128 v[166:169], v250 offset:17408
	ds_read_b128 v[170:173], v250 offset:18432
	ds_read_b128 v[174:177], v250 offset:19456
	ds_read_b128 v[178:181], v250 offset:20480
	ds_read_b128 v[182:185], v250 offset:21504
	ds_read_b128 v[186:189], v250 offset:22528
	ds_read_b128 v[190:193], v250 offset:23552
	global_load_lds_dwordx4 v[214:215], off
	s_add_i32 m0, s2, 0x2000
	s_add_u32 s2, s26, 0xb0000
	v_lshl_add_u64 v[216:217], s[26:27], 0, v[204:205]
	s_addc_u32 s3, s27, 0
	s_add_i32 s52, s53, s31
	global_load_lds_dwordx4 v[216:217], off
	v_lshl_add_u64 v[218:219], s[2:3], 0, v[32:33]
	s_mov_b32 m0, s52
	v_lshl_add_u64 v[220:221], s[28:29], 0, v[206:207]
	global_load_lds_dwordx4 v[218:219], off
	v_lshl_add_u64 v[218:219], s[2:3], 0, v[204:205]
	s_add_i32 m0, s52, 0x2000
	s_nop 0
	global_load_lds_dwordx4 v[218:219], off
	v_lshl_add_u64 v[218:219], s[28:29], 0, v[208:209]
	s_mov_b32 m0, s38
	s_nop 0
	global_load_lds_dwordx4 v[218:219], off
	s_mov_b32 m0, s39
	s_nop 0
	global_load_lds_dwordx4 v[220:221], off
	s_waitcnt vmcnt(8)
	s_waitcnt lgkmcnt(0)
	s_barrier
; #define PG8_STAGE(bufoff, gbase, voff) do { _Pragma("unroll") for (int _i = 0; _i < 2; ++_i) \
;         __builtin_amdgcn_global_load_lds((const unsigned*)((const char*)(gbase) + (voff)[_i]), (PG8_LAS unsigned*)(lds + (bufoff) + ldsw + _i * 8192), 16, 0, 0); } while (0)
; #define PG8_LDA(dst, b, h) do { _Pragma("unroll") for (int m = 0; m < 4; ++m) _Pragma("unroll") for (int k = 0; k < 2; ++k) dst[m][k] = *(const PG8_LAS bf16x8*)(lds + PG8_SA(b, h) + aoff + m * 2048 + k * 1024); } while (0)
; #define PG8_LDB(dst, b, h) do { _Pragma("unroll") for (int n = 0; n < 2; ++n) _Pragma("unroll") for (int k = 0; k < 2; ++k) dst[n][k] = *(const PG8_LAS bf16x8*)(lds + PG8_SB(b, h) + boff + n * 2048 + k * 1024); } while (0)
; #define PG8_MMA(ai, bj, At, Bt) do { __builtin_amdgcn_s_setprio(1); _Pragma("unroll") for (int m = 0; m < 4; ++m) _Pragma("unroll") for (int n = 0; n < 2; ++n) _Pragma("unroll") for (int k = 0; k < 2; ++k) \
;         acc[ai][bj][m][n] = __builtin_amdgcn_mfma_f32_16x16x32_bf16(Bt[n][k], At[m][k], acc[ai][bj][m][n], 0, 0, 0); __builtin_amdgcn_s_setprio(0); } while (0)
; #define PG8_WAIT_V(n) asm volatile("s_waitcnt vmcnt(" #n ")" ::: "memory")
; #define PG8_WAIT_L(n) asm volatile("s_waitcnt lgkmcnt(" #n ")" ::: "memory")
; #define PG8_BAR __builtin_amdgcn_s_barrier()
; #define PG8_SCHED __builtin_amdgcn_sched_barrier(0)
; template <class Epi, class Sched, bool ALIGN_EPI = false, bool SP2 = false>
; __device__ __forceinline__ void gemm_phase(PG8_LAS unsigned char* lds, const Gemm g, const Sched& S, const Epi& E, int tid_in) {
;     ...
;             PG8_WAIT_V(8); PG8_WAIT_L(0); PG8_BAR; PG8_MMA(1, 0, At, B0); PG8_MMA(1, 1, At, B1); PG8_BAR; PG8_SCHED;
;             PG8_LDB(B0, 1, 0); PG8_LDB(B1, 1, 1); PG8_SCHED; PG8_LDA(At, 1, 0); PG8_STAGE(PG8_SA(0, 1), a2 + hstep, voffA);
;             PG8_WAIT_V(8); PG8_WAIT_L(0); PG8_BAR; PG8_MMA(0, 0, At, B0); PG8_MMA(0, 1, At, B1); PG8_BAR; PG8_SCHED;
	s_setprio 1
	s_waitcnt lgkmcnt(0)
	v_mfma_f32_16x16x32_bf16 v[62:65], v[130:133], v[162:165], v[62:65]
	v_mfma_f32_16x16x32_bf16 v[58:61], v[138:141], v[162:165], v[58:61]
	v_mfma_f32_16x16x32_bf16 v[50:53], v[130:133], v[170:173], v[50:53]
	v_mfma_f32_16x16x32_bf16 v[42:45], v[138:141], v[170:173], v[42:45]
	v_mfma_f32_16x16x32_bf16 v[34:37], v[130:133], v[178:181], v[34:37]
	v_mfma_f32_16x16x32_bf16 v[24:27], v[138:141], v[178:181], v[24:27]
	v_mfma_f32_16x16x32_bf16 v[16:19], v[130:133], v[186:189], v[16:19]
	v_mfma_f32_16x16x32_bf16 v[8:11], v[138:141], v[186:189], v[8:11]
	v_mfma_f32_16x16x32_bf16 v[62:65], v[134:137], v[166:169], v[62:65]
	v_mfma_f32_16x16x32_bf16 v[58:61], v[142:145], v[166:169], v[58:61]
	v_mfma_f32_16x16x32_bf16 v[50:53], v[134:137], v[174:177], v[50:53]
	v_mfma_f32_16x16x32_bf16 v[42:45], v[142:145], v[174:177], v[42:45]
	v_mfma_f32_16x16x32_bf16 v[34:37], v[134:137], v[182:185], v[34:37]
	v_mfma_f32_16x16x32_bf16 v[24:27], v[142:145], v[182:185], v[24:27]
	v_mfma_f32_16x16x32_bf16 v[16:19], v[134:137], v[190:193], v[16:19]
	v_mfma_f32_16x16x32_bf16 v[8:11], v[142:145], v[190:193], v[8:11]
	v_mfma_f32_16x16x32_bf16 v[54:57], v[146:149], v[162:165], v[54:57]
	v_mfma_f32_16x16x32_bf16 v[46:49], v[154:157], v[162:165], v[46:49]
	v_mfma_f32_16x16x32_bf16 v[38:41], v[146:149], v[170:173], v[38:41]
	v_mfma_f32_16x16x32_bf16 v[28:31], v[154:157], v[170:173], v[28:31]
	v_mfma_f32_16x16x32_bf16 v[20:23], v[146:149], v[178:181], v[20:23]
	v_mfma_f32_16x16x32_bf16 v[12:15], v[154:157], v[178:181], v[12:15]
	v_mfma_f32_16x16x32_bf16 v[4:7], v[146:149], v[186:189], v[4:7]
	v_mfma_f32_16x16x32_bf16 v[0:3], v[154:157], v[186:189], v[0:3]
	v_mfma_f32_16x16x32_bf16 v[54:57], v[150:153], v[166:169], v[54:57]
	v_mfma_f32_16x16x32_bf16 v[46:49], v[158:161], v[166:169], v[46:49]
	v_mfma_f32_16x16x32_bf16 v[38:41], v[150:153], v[174:177], v[38:41]
	v_mfma_f32_16x16x32_bf16 v[28:31], v[158:161], v[174:177], v[28:31]
	v_mfma_f32_16x16x32_bf16 v[20:23], v[150:153], v[182:185], v[20:23]
	v_mfma_f32_16x16x32_bf16 v[12:15], v[158:161], v[182:185], v[12:15]
	v_mfma_f32_16x16x32_bf16 v[4:7], v[150:153], v[190:193], v[4:7]
	v_mfma_f32_16x16x32_bf16 v[0:3], v[158:161], v[190:193], v[0:3]
	s_setprio 0
	s_barrier
	s_add_i32 s52, 0, 0x18000
	s_add_i32 s53, 0, 0x1c000
	v_add_u32_e32 v142, s52, v248
	v_add_u32_e32 v158, s53, v248
	ds_read_b128 v[130:133], v142
	ds_read_b128 v[134:137], v142 offset:1024
	ds_read_b128 v[138:141], v142 offset:2048
	ds_read_b128 v[142:145], v142 offset:3072
	ds_read_b128 v[146:149], v158
	ds_read_b128 v[150:153], v158 offset:1024
	ds_read_b128 v[154:157], v158 offset:2048
	ds_read_b128 v[158:161], v158 offset:3072
	s_add_u32 s2, s28, 0xb0000
	s_addc_u32 s3, s29, 0
	s_mov_b32 m0, s40
	v_lshl_add_u64 v[222:223], s[2:3], 0, v[208:209]
	ds_read_b128 v[162:165], v250 offset:32768
	ds_read_b128 v[166:169], v250 offset:33792
	ds_read_b128 v[170:173], v250 offset:34816
	ds_read_b128 v[174:177], v250 offset:35840
	ds_read_b128 v[178:181], v250 offset:36864
	ds_read_b128 v[182:185], v250 offset:37888
	ds_read_b128 v[186:189], v250 offset:38912
	ds_read_b128 v[190:193], v250 offset:39936
	global_load_lds_dwordx4 v[222:223], off
	v_lshl_add_u64 v[222:223], s[2:3], 0, v[206:207]
	s_mov_b32 m0, s41
	s_nop 0
	global_load_lds_dwordx4 v[222:223], off
	s_waitcnt vmcnt(8)
	s_waitcnt lgkmcnt(0)
	s_barrier
	s_setprio 1
	s_waitcnt lgkmcnt(0)
	v_mfma_f32_16x16x32_bf16 v[126:129], v[130:133], v[162:165], v[126:129]
	v_mfma_f32_16x16x32_bf16 v[122:125], v[138:141], v[162:165], v[122:125]
	v_mfma_f32_16x16x32_bf16 v[114:117], v[130:133], v[170:173], v[114:117]
	v_mfma_f32_16x16x32_bf16 v[106:109], v[138:141], v[170:173], v[106:109]
	v_mfma_f32_16x16x32_bf16 v[98:101], v[130:133], v[178:181], v[98:101]
	v_mfma_f32_16x16x32_bf16 v[90:93], v[138:141], v[178:181], v[90:93]
	v_mfma_f32_16x16x32_bf16 v[82:85], v[130:133], v[186:189], v[82:85]
	v_mfma_f32_16x16x32_bf16 v[74:77], v[138:141], v[186:189], v[74:77]
	v_mfma_f32_16x16x32_bf16 v[126:129], v[134:137], v[166:169], v[126:129]
	v_mfma_f32_16x16x32_bf16 v[122:125], v[142:145], v[166:169], v[122:125]
	v_mfma_f32_16x16x32_bf16 v[114:117], v[134:137], v[174:177], v[114:117]
	v_mfma_f32_16x16x32_bf16 v[106:109], v[142:145], v[174:177], v[106:109]
	v_mfma_f32_16x16x32_bf16 v[98:101], v[134:137], v[182:185], v[98:101]
	v_mfma_f32_16x16x32_bf16 v[90:93], v[142:145], v[182:185], v[90:93]
	v_mfma_f32_16x16x32_bf16 v[82:85], v[134:137], v[190:193], v[82:85]
	v_mfma_f32_16x16x32_bf16 v[74:77], v[142:145], v[190:193], v[74:77]
	v_mfma_f32_16x16x32_bf16 v[118:121], v[146:149], v[162:165], v[118:121]
	v_mfma_f32_16x16x32_bf16 v[110:113], v[154:157], v[162:165], v[110:113]
	v_mfma_f32_16x16x32_bf16 v[102:105], v[146:149], v[170:173], v[102:105]
	v_mfma_f32_16x16x32_bf16 v[94:97], v[154:157], v[170:173], v[94:97]
	v_mfma_f32_16x16x32_bf16 v[86:89], v[146:149], v[178:181], v[86:89]
	v_mfma_f32_16x16x32_bf16 v[78:81], v[154:157], v[178:181], v[78:81]
	v_mfma_f32_16x16x32_bf16 v[70:73], v[146:149], v[186:189], v[70:73]
	v_mfma_f32_16x16x32_bf16 v[66:69], v[154:157], v[186:189], v[66:69]
	v_mfma_f32_16x16x32_bf16 v[118:121], v[150:153], v[166:169], v[118:121]
	v_mfma_f32_16x16x32_bf16 v[110:113], v[158:161], v[166:169], v[110:113]
	v_mfma_f32_16x16x32_bf16 v[102:105], v[150:153], v[174:177], v[102:105]
	v_mfma_f32_16x16x32_bf16 v[94:97], v[158:161], v[174:177], v[94:97]
	v_mfma_f32_16x16x32_bf16 v[86:89], v[150:153], v[182:185], v[86:89]
	v_mfma_f32_16x16x32_bf16 v[78:81], v[158:161], v[182:185], v[78:81]
	v_mfma_f32_16x16x32_bf16 v[70:73], v[150:153], v[190:193], v[70:73]
	v_mfma_f32_16x16x32_bf16 v[66:69], v[158:161], v[190:193], v[66:69]
	s_setprio 0
	s_barrier
; #define PG8_STAGE(bufoff, gbase, voff) do { _Pragma("unroll") for (int _i = 0; _i < 2; ++_i) \
;         __builtin_amdgcn_global_load_lds((const unsigned*)((const char*)(gbase) + (voff)[_i]), (PG8_LAS unsigned*)(lds + (bufoff) + ldsw + _i * 8192), 16, 0, 0); } while (0)
; #define PG8_LDA(dst, b, h) do { _Pragma("unroll") for (int m = 0; m < 4; ++m) _Pragma("unroll") for (int k = 0; k < 2; ++k) dst[m][k] = *(const PG8_LAS bf16x8*)(lds + PG8_SA(b, h) + aoff + m * 2048 + k * 1024); } while (0)
; #define PG8_MMA(ai, bj, At, Bt) do { __builtin_amdgcn_s_setprio(1); _Pragma("unroll") for (int m = 0; m < 4; ++m) _Pragma("unroll") for (int n = 0; n < 2; ++n) _Pragma("unroll") for (int k = 0; k < 2; ++k) \
;         acc[ai][bj][m][n] = __builtin_amdgcn_mfma_f32_16x16x32_bf16(Bt[n][k], At[m][k], acc[ai][bj][m][n], 0, 0, 0); __builtin_amdgcn_s_setprio(0); } while (0)
; #define PG8_WAIT_V(n) asm volatile("s_waitcnt vmcnt(" #n ")" ::: "memory")
; #define PG8_WAIT_L(n) asm volatile("s_waitcnt lgkmcnt(" #n ")" ::: "memory")
; #define PG8_BAR __builtin_amdgcn_s_barrier()
; #define PG8_SCHED __builtin_amdgcn_sched_barrier(0)
; template <class Epi, class Sched, bool ALIGN_EPI = false, bool SP2 = false>
; __device__ __forceinline__ void gemm_phase(PG8_LAS unsigned char* lds, const Gemm g, const Sched& S, const Epi& E, int tid_in) {
;     ...
;             PG8_LDA(At, 1, 1); PG8_STAGE(PG8_SB(1, 0), b3, voffB); PG8_STAGE(PG8_SB(1, 1), b3 + hstep, voffB); PG8_STAGE(PG8_SA(1, 0), a3, voffA);
;             PG8_WAIT_V(8); PG8_WAIT_L(0); PG8_BAR; PG8_MMA(1, 0, At, B0); PG8_MMA(1, 1, At, B1); PG8_BAR; PG8_SCHED;
;     ...
;         if constexpr (ALIGN_EPI) { if (wr == 0) PG8_BAR; }
	s_add_i32 s2, s52, s31
	v_lshl_add_u64 v[214:215], v[214:215], 0, s[84:85]
	s_mov_b32 m0, s2
	ds_read_b128 v[162:165], v250 offset:49152
	ds_read_b128 v[166:169], v250 offset:50176
	ds_read_b128 v[170:173], v250 offset:51200
	ds_read_b128 v[174:177], v250 offset:52224
	ds_read_b128 v[178:181], v250 offset:53248
	ds_read_b128 v[182:185], v250 offset:54272
	ds_read_b128 v[186:189], v250 offset:55296
	ds_read_b128 v[190:193], v250 offset:56320
	global_load_lds_dwordx4 v[214:215], off
	s_add_i32 m0, s2, 0x2000
	s_add_u32 s2, s26, 0xb0080
	v_lshl_add_u64 v[214:215], v[216:217], 0, s[84:85]
	s_addc_u32 s3, s27, 0
	s_add_i32 s26, s53, s31
	global_load_lds_dwordx4 v[214:215], off
	v_lshl_add_u64 v[214:215], s[2:3], 0, v[32:33]
	s_mov_b32 m0, s26
	s_nop 0
	global_load_lds_dwordx4 v[214:215], off
	v_lshl_add_u64 v[214:215], s[2:3], 0, v[204:205]
	s_add_i32 m0, s26, 0x2000
	s_nop 0
	global_load_lds_dwordx4 v[214:215], off
	v_lshl_add_u64 v[214:215], v[218:219], 0, s[84:85]
	s_mov_b32 m0, s42
	s_nop 0
	global_load_lds_dwordx4 v[214:215], off
	v_lshl_add_u64 v[214:215], v[220:221], 0, s[84:85]
	s_mov_b32 m0, s43
	s_nop 0
	global_load_lds_dwordx4 v[214:215], off
	s_waitcnt vmcnt(8)
	s_waitcnt lgkmcnt(0)
	s_barrier
	s_setprio 1
	s_waitcnt lgkmcnt(0)
	v_mfma_f32_16x16x32_bf16 v[62:65], v[130:133], v[162:165], v[62:65]
	v_mfma_f32_16x16x32_bf16 v[58:61], v[138:141], v[162:165], v[58:61]
	v_mfma_f32_16x16x32_bf16 v[50:53], v[130:133], v[170:173], v[50:53]
	v_mfma_f32_16x16x32_bf16 v[42:45], v[138:141], v[170:173], v[42:45]
	v_mfma_f32_16x16x32_bf16 v[34:37], v[130:133], v[178:181], v[34:37]
	v_mfma_f32_16x16x32_bf16 v[24:27], v[138:141], v[178:181], v[24:27]
	v_mfma_f32_16x16x32_bf16 v[16:19], v[130:133], v[186:189], v[16:19]
	v_mfma_f32_16x16x32_bf16 v[8:11], v[138:141], v[186:189], v[8:11]
	v_mfma_f32_16x16x32_bf16 v[62:65], v[134:137], v[166:169], v[62:65]
	v_mfma_f32_16x16x32_bf16 v[58:61], v[142:145], v[166:169], v[58:61]
	v_mfma_f32_16x16x32_bf16 v[50:53], v[134:137], v[174:177], v[50:53]
	v_mfma_f32_16x16x32_bf16 v[42:45], v[142:145], v[174:177], v[42:45]
	v_mfma_f32_16x16x32_bf16 v[34:37], v[134:137], v[182:185], v[34:37]
	v_mfma_f32_16x16x32_bf16 v[24:27], v[142:145], v[182:185], v[24:27]
	v_mfma_f32_16x16x32_bf16 v[16:19], v[134:137], v[190:193], v[16:19]
	v_mfma_f32_16x16x32_bf16 v[8:11], v[142:145], v[190:193], v[8:11]
	v_mfma_f32_16x16x32_bf16 v[54:57], v[146:149], v[162:165], v[54:57]
	v_mfma_f32_16x16x32_bf16 v[46:49], v[154:157], v[162:165], v[46:49]
	v_mfma_f32_16x16x32_bf16 v[38:41], v[146:149], v[170:173], v[38:41]
	v_mfma_f32_16x16x32_bf16 v[28:31], v[154:157], v[170:173], v[28:31]
	v_mfma_f32_16x16x32_bf16 v[20:23], v[146:149], v[178:181], v[20:23]
	v_mfma_f32_16x16x32_bf16 v[12:15], v[154:157], v[178:181], v[12:15]
	v_mfma_f32_16x16x32_bf16 v[4:7], v[146:149], v[186:189], v[4:7]
	v_mfma_f32_16x16x32_bf16 v[0:3], v[154:157], v[186:189], v[0:3]
	v_mfma_f32_16x16x32_bf16 v[54:57], v[150:153], v[166:169], v[54:57]
	v_mfma_f32_16x16x32_bf16 v[46:49], v[158:161], v[166:169], v[46:49]
	v_mfma_f32_16x16x32_bf16 v[38:41], v[150:153], v[174:177], v[38:41]
	v_mfma_f32_16x16x32_bf16 v[28:31], v[158:161], v[174:177], v[28:31]
	v_mfma_f32_16x16x32_bf16 v[20:23], v[150:153], v[182:185], v[20:23]
	v_mfma_f32_16x16x32_bf16 v[12:15], v[158:161], v[182:185], v[12:15]
	v_mfma_f32_16x16x32_bf16 v[4:7], v[150:153], v[190:193], v[4:7]
	v_mfma_f32_16x16x32_bf16 v[0:3], v[158:161], v[190:193], v[0:3]
	s_setprio 0
	s_barrier
	s_add_i32 s51, s51, 2
	s_add_u32 s49, s49, 0x100
	s_addc_u32 s50, s50, 0
	s_cmp_gt_u32 s51, 41
	s_mov_b64 s[2:3], s[6:7]
	s_cbranch_scc0 .LBB0_1010
	s_and_b64 vcc, exec, s[18:19]
	s_cbranch_vccz .LBB0_1013
	s_barrier
